# v9 + lever 9: loop counter / pointer SALU block of the six GEMM K loops moved in front of the closing s_setprio/s_barrier (MFMA shadow)
# baseline (speedup 1.0000x reference)
.LBB0_207:
	ds_read_b128 v[152:155], v168
	ds_read_b128 v[156:159], v168 offset:1024
	ds_read_b128 v[172:175], v168 offset:2048
	ds_read_b128 v[176:179], v168 offset:3072
	ds_read_b128 v[180:183], v169
	ds_read_b128 v[186:189], v169 offset:1024
	ds_read_b128 v[190:193], v169 offset:2048
	ds_read_b128 v[194:197], v169 offset:3072
	s_add_i32 s12, s8, 2
	s_add_u32 s13, s6, 0x80
	s_addc_u32 s9, s7, 0
	s_cmp_eq_u32 s52, s8
	s_cselect_b32 s8, s86, s13
	s_cselect_b32 s9, s87, s9
	s_cselect_b32 s17, s89, s11
	s_cselect_b32 s16, s88, s10
	v_lshl_add_u64 v[160:161], s[6:7], 0, v[144:145]
	s_add_i32 m0, s90, 0xc000
	ds_read_b128 v[198:201], v170
	ds_read_b128 v[202:205], v170 offset:1024
	ds_read_b128 v[206:209], v170 offset:2048
	ds_read_b128 v[210:213], v170 offset:3072
	ds_read_b128 v[214:217], v170 offset:4096
	ds_read_b128 v[224:227], v170 offset:5120
	ds_read_b128 v[228:231], v170 offset:6144
	ds_read_b128 v[232:235], v170 offset:7168
	global_load_lds_dwordx4 v[160:161], off
	v_lshl_add_u64 v[160:161], s[6:7], 0, v[146:147]
	s_add_i32 m0, s90, 0xe000
	s_nop 0
	global_load_lds_dwordx4 v[160:161], off
	s_waitcnt vmcnt(8)
	s_waitcnt lgkmcnt(0)
	s_barrier
	s_setprio 1
	s_waitcnt lgkmcnt(0)
	v_mfma_f32_16x16x32_bf16 v[124:127], v[152:155], v[198:201], v[124:127]
	v_mfma_f32_16x16x32_bf16 v[120:123], v[172:175], v[198:201], v[120:123]
	v_mfma_f32_16x16x32_bf16 v[108:111], v[152:155], v[206:209], v[108:111]
	v_mfma_f32_16x16x32_bf16 v[104:107], v[172:175], v[206:209], v[104:107]
	v_mfma_f32_16x16x32_bf16 v[92:95], v[152:155], v[214:217], v[92:95]
	v_mfma_f32_16x16x32_bf16 v[88:91], v[172:175], v[214:217], v[88:91]
	v_mfma_f32_16x16x32_bf16 v[76:79], v[152:155], v[228:231], v[76:79]
	v_mfma_f32_16x16x32_bf16 v[72:75], v[172:175], v[228:231], v[72:75]
	v_mfma_f32_16x16x32_bf16 v[124:127], v[156:159], v[202:205], v[124:127]
	v_mfma_f32_16x16x32_bf16 v[120:123], v[176:179], v[202:205], v[120:123]
	v_mfma_f32_16x16x32_bf16 v[108:111], v[156:159], v[210:213], v[108:111]
	v_mfma_f32_16x16x32_bf16 v[104:107], v[176:179], v[210:213], v[104:107]
	v_mfma_f32_16x16x32_bf16 v[92:95], v[156:159], v[224:227], v[92:95]
	v_mfma_f32_16x16x32_bf16 v[88:91], v[176:179], v[224:227], v[88:91]
	v_mfma_f32_16x16x32_bf16 v[76:79], v[156:159], v[232:235], v[76:79]
	v_mfma_f32_16x16x32_bf16 v[72:75], v[176:179], v[232:235], v[72:75]
	s_setprio 0
	s_setprio 1
	v_mfma_f32_16x16x32_bf16 v[116:119], v[180:183], v[198:201], v[116:119]
	v_mfma_f32_16x16x32_bf16 v[112:115], v[190:193], v[198:201], v[112:115]
	v_mfma_f32_16x16x32_bf16 v[100:103], v[180:183], v[206:209], v[100:103]
	v_mfma_f32_16x16x32_bf16 v[96:99], v[190:193], v[206:209], v[96:99]
	v_mfma_f32_16x16x32_bf16 v[84:87], v[180:183], v[214:217], v[84:87]
	v_mfma_f32_16x16x32_bf16 v[80:83], v[190:193], v[214:217], v[80:83]
	v_mfma_f32_16x16x32_bf16 v[68:71], v[180:183], v[228:231], v[68:71]
	v_mfma_f32_16x16x32_bf16 v[64:67], v[190:193], v[228:231], v[64:67]
	v_mfma_f32_16x16x32_bf16 v[116:119], v[186:189], v[202:205], v[116:119]
	v_mfma_f32_16x16x32_bf16 v[112:115], v[194:197], v[202:205], v[112:115]
	v_mfma_f32_16x16x32_bf16 v[100:103], v[186:189], v[210:213], v[100:103]
	v_mfma_f32_16x16x32_bf16 v[96:99], v[194:197], v[210:213], v[96:99]
	v_mfma_f32_16x16x32_bf16 v[84:87], v[186:189], v[224:227], v[84:87]
	v_mfma_f32_16x16x32_bf16 v[80:83], v[194:197], v[224:227], v[80:83]
	v_mfma_f32_16x16x32_bf16 v[68:71], v[186:189], v[232:235], v[68:71]
	v_mfma_f32_16x16x32_bf16 v[64:67], v[194:197], v[232:235], v[64:67]
	s_setprio 0
	s_barrier
	s_add_i32 s13, s37, s31
	v_lshl_add_u64 v[160:161], s[16:17], 0, v[130:131]
	s_mov_b32 m0, s13
	ds_read_b128 v[198:201], v170 offset:16384
	ds_read_b128 v[202:205], v170 offset:17408
	ds_read_b128 v[206:209], v170 offset:18432
	ds_read_b128 v[210:213], v170 offset:19456
	ds_read_b128 v[214:217], v170 offset:20480
	ds_read_b128 v[224:227], v170 offset:21504
	ds_read_b128 v[228:231], v170 offset:22528
	ds_read_b128 v[232:235], v170 offset:23552
	global_load_lds_dwordx4 v[160:161], off
	s_add_i32 m0, s13, 0x2000
	v_lshl_add_u64 v[236:237], s[16:17], 0, v[134:135]
	s_add_u32 s16, s16, s74
	s_addc_u32 s17, s17, s75
	s_add_i32 s13, s38, s31
	global_load_lds_dwordx4 v[236:237], off
	v_lshl_add_u64 v[238:239], s[16:17], 0, v[130:131]
	s_mov_b32 m0, s13
	v_lshl_add_u64 v[240:241], s[16:17], 0, v[134:135]
	global_load_lds_dwordx4 v[238:239], off
	s_add_i32 m0, s13, 0x2000
	v_lshl_add_u64 v[242:243], s[8:9], 0, v[128:129]
	global_load_lds_dwordx4 v[240:241], off
	s_mov_b32 m0, s90
	v_lshl_add_u64 v[244:245], s[8:9], 0, v[132:133]
	global_load_lds_dwordx4 v[242:243], off
	s_mov_b32 m0, s91
	s_nop 0
	global_load_lds_dwordx4 v[244:245], off
	s_waitcnt vmcnt(8)
	s_waitcnt lgkmcnt(0)
	s_barrier
	s_setprio 1
	s_waitcnt lgkmcnt(0)
	v_mfma_f32_16x16x32_bf16 v[60:63], v[152:155], v[198:201], v[60:63]
	v_mfma_f32_16x16x32_bf16 v[56:59], v[172:175], v[198:201], v[56:59]
	v_mfma_f32_16x16x32_bf16 v[44:47], v[152:155], v[206:209], v[44:47]
	v_mfma_f32_16x16x32_bf16 v[40:43], v[172:175], v[206:209], v[40:43]
	v_mfma_f32_16x16x32_bf16 v[28:31], v[152:155], v[214:217], v[28:31]
	v_mfma_f32_16x16x32_bf16 v[24:27], v[172:175], v[214:217], v[24:27]
	v_mfma_f32_16x16x32_bf16 v[12:15], v[152:155], v[228:231], v[12:15]
	v_mfma_f32_16x16x32_bf16 v[8:11], v[172:175], v[228:231], v[8:11]
	v_mfma_f32_16x16x32_bf16 v[60:63], v[156:159], v[202:205], v[60:63]
	v_mfma_f32_16x16x32_bf16 v[56:59], v[176:179], v[202:205], v[56:59]
	v_mfma_f32_16x16x32_bf16 v[44:47], v[156:159], v[210:213], v[44:47]
	v_mfma_f32_16x16x32_bf16 v[40:43], v[176:179], v[210:213], v[40:43]
	v_mfma_f32_16x16x32_bf16 v[28:31], v[156:159], v[224:227], v[28:31]
	v_mfma_f32_16x16x32_bf16 v[24:27], v[176:179], v[224:227], v[24:27]
	v_mfma_f32_16x16x32_bf16 v[12:15], v[156:159], v[232:235], v[12:15]
	v_mfma_f32_16x16x32_bf16 v[8:11], v[176:179], v[232:235], v[8:11]
	s_setprio 0
	s_setprio 1
	v_mfma_f32_16x16x32_bf16 v[52:55], v[180:183], v[198:201], v[52:55]
	v_mfma_f32_16x16x32_bf16 v[48:51], v[190:193], v[198:201], v[48:51]
	v_mfma_f32_16x16x32_bf16 v[36:39], v[180:183], v[206:209], v[36:39]
	v_mfma_f32_16x16x32_bf16 v[32:35], v[190:193], v[206:209], v[32:35]
	v_mfma_f32_16x16x32_bf16 v[20:23], v[180:183], v[214:217], v[20:23]
	v_mfma_f32_16x16x32_bf16 v[16:19], v[190:193], v[214:217], v[16:19]
	v_mfma_f32_16x16x32_bf16 v[4:7], v[180:183], v[228:231], v[4:7]
	v_mfma_f32_16x16x32_bf16 v[0:3], v[190:193], v[228:231], v[0:3]
	v_mfma_f32_16x16x32_bf16 v[52:55], v[186:189], v[202:205], v[52:55]
	v_mfma_f32_16x16x32_bf16 v[48:51], v[194:197], v[202:205], v[48:51]
	v_mfma_f32_16x16x32_bf16 v[36:39], v[186:189], v[210:213], v[36:39]
	v_mfma_f32_16x16x32_bf16 v[32:35], v[194:197], v[210:213], v[32:35]
	v_mfma_f32_16x16x32_bf16 v[20:23], v[186:189], v[224:227], v[20:23]
	v_mfma_f32_16x16x32_bf16 v[16:19], v[194:197], v[224:227], v[16:19]
	v_mfma_f32_16x16x32_bf16 v[4:7], v[186:189], v[232:235], v[4:7]
	v_mfma_f32_16x16x32_bf16 v[0:3], v[194:197], v[232:235], v[0:3]
	s_setprio 0
	s_barrier
	s_add_i32 s13, 0, 0x18000
	v_add_u32_e32 v136, s13, v143
	s_add_i32 s16, 0, 0x1c000
	ds_read_b128 v[152:155], v136
	ds_read_b128 v[156:159], v136 offset:1024
	ds_read_b128 v[172:175], v136 offset:2048
	ds_read_b128 v[176:179], v136 offset:3072
	v_add_u32_e32 v136, s16, v143
	ds_read_b128 v[180:183], v136
	ds_read_b128 v[186:189], v136 offset:1024
	ds_read_b128 v[190:193], v136 offset:2048
	ds_read_b128 v[194:197], v136 offset:3072
	s_add_u32 s8, s8, s74
	s_addc_u32 s9, s9, s75
	s_mov_b32 m0, s78
	v_lshl_add_u64 v[246:247], s[8:9], 0, v[128:129]
	ds_read_b128 v[198:201], v170 offset:32768
	ds_read_b128 v[202:205], v170 offset:33792
	ds_read_b128 v[206:209], v170 offset:34816
	ds_read_b128 v[210:213], v170 offset:35840
	ds_read_b128 v[214:217], v170 offset:36864
	ds_read_b128 v[224:227], v170 offset:37888
	ds_read_b128 v[228:231], v170 offset:38912
	ds_read_b128 v[232:235], v170 offset:39936
	global_load_lds_dwordx4 v[246:247], off
	v_lshl_add_u64 v[246:247], s[8:9], 0, v[132:133]
	s_mov_b32 m0, s79
	s_nop 0
	global_load_lds_dwordx4 v[246:247], off
	s_waitcnt vmcnt(8)
	s_waitcnt lgkmcnt(0)
	s_barrier
	s_setprio 1
	s_waitcnt lgkmcnt(0)
	v_mfma_f32_16x16x32_bf16 v[124:127], v[152:155], v[198:201], v[124:127]
	v_mfma_f32_16x16x32_bf16 v[120:123], v[172:175], v[198:201], v[120:123]
	v_mfma_f32_16x16x32_bf16 v[108:111], v[152:155], v[206:209], v[108:111]
	v_mfma_f32_16x16x32_bf16 v[104:107], v[172:175], v[206:209], v[104:107]
	v_mfma_f32_16x16x32_bf16 v[92:95], v[152:155], v[214:217], v[92:95]
	v_mfma_f32_16x16x32_bf16 v[88:91], v[172:175], v[214:217], v[88:91]
	v_mfma_f32_16x16x32_bf16 v[76:79], v[152:155], v[228:231], v[76:79]
	v_mfma_f32_16x16x32_bf16 v[72:75], v[172:175], v[228:231], v[72:75]
	v_mfma_f32_16x16x32_bf16 v[124:127], v[156:159], v[202:205], v[124:127]
	v_mfma_f32_16x16x32_bf16 v[120:123], v[176:179], v[202:205], v[120:123]
	v_mfma_f32_16x16x32_bf16 v[108:111], v[156:159], v[210:213], v[108:111]
	v_mfma_f32_16x16x32_bf16 v[104:107], v[176:179], v[210:213], v[104:107]
	v_mfma_f32_16x16x32_bf16 v[92:95], v[156:159], v[224:227], v[92:95]
	v_mfma_f32_16x16x32_bf16 v[88:91], v[176:179], v[224:227], v[88:91]
	v_mfma_f32_16x16x32_bf16 v[76:79], v[156:159], v[232:235], v[76:79]
	v_mfma_f32_16x16x32_bf16 v[72:75], v[176:179], v[232:235], v[72:75]
	s_setprio 0
	s_setprio 1
	v_mfma_f32_16x16x32_bf16 v[116:119], v[180:183], v[198:201], v[116:119]
	v_mfma_f32_16x16x32_bf16 v[112:115], v[190:193], v[198:201], v[112:115]
	v_mfma_f32_16x16x32_bf16 v[100:103], v[180:183], v[206:209], v[100:103]
	v_mfma_f32_16x16x32_bf16 v[96:99], v[190:193], v[206:209], v[96:99]
	v_mfma_f32_16x16x32_bf16 v[84:87], v[180:183], v[214:217], v[84:87]
	v_mfma_f32_16x16x32_bf16 v[80:83], v[190:193], v[214:217], v[80:83]
	v_mfma_f32_16x16x32_bf16 v[68:71], v[180:183], v[228:231], v[68:71]
	v_mfma_f32_16x16x32_bf16 v[64:67], v[190:193], v[228:231], v[64:67]
	v_mfma_f32_16x16x32_bf16 v[116:119], v[186:189], v[202:205], v[116:119]
	v_mfma_f32_16x16x32_bf16 v[112:115], v[194:197], v[202:205], v[112:115]
	v_mfma_f32_16x16x32_bf16 v[100:103], v[186:189], v[210:213], v[100:103]
	v_mfma_f32_16x16x32_bf16 v[96:99], v[194:197], v[210:213], v[96:99]
	v_mfma_f32_16x16x32_bf16 v[84:87], v[186:189], v[224:227], v[84:87]
	v_mfma_f32_16x16x32_bf16 v[80:83], v[194:197], v[224:227], v[80:83]
	v_mfma_f32_16x16x32_bf16 v[68:71], v[186:189], v[232:235], v[68:71]
	v_mfma_f32_16x16x32_bf16 v[64:67], v[194:197], v[232:235], v[64:67]
	s_setprio 0
	s_barrier
	s_add_i32 s8, s13, s31
	v_lshl_add_u64 v[160:161], v[160:161], 0, s[92:93]
	s_mov_b32 m0, s8
	ds_read_b128 v[198:201], v170 offset:49152
	ds_read_b128 v[202:205], v170 offset:50176
	ds_read_b128 v[206:209], v170 offset:51200
	ds_read_b128 v[210:213], v170 offset:52224
	ds_read_b128 v[214:217], v170 offset:53248
	ds_read_b128 v[224:227], v170 offset:54272
	ds_read_b128 v[228:231], v170 offset:55296
	ds_read_b128 v[232:235], v170 offset:56320
	global_load_lds_dwordx4 v[160:161], off
	v_lshl_add_u64 v[160:161], v[236:237], 0, s[92:93]
	s_add_i32 m0, s8, 0x2000
	s_add_i32 s8, s16, s31
	global_load_lds_dwordx4 v[160:161], off
	v_lshl_add_u64 v[160:161], v[238:239], 0, s[92:93]
	s_mov_b32 m0, s8
	s_nop 0
	global_load_lds_dwordx4 v[160:161], off
	v_lshl_add_u64 v[160:161], v[240:241], 0, s[92:93]
	s_add_i32 m0, s8, 0x2000
	s_nop 0
	global_load_lds_dwordx4 v[160:161], off
	v_lshl_add_u64 v[160:161], v[242:243], 0, s[92:93]
	s_mov_b32 m0, s33
	s_nop 0
	global_load_lds_dwordx4 v[160:161], off
	v_lshl_add_u64 v[160:161], v[244:245], 0, s[92:93]
	s_mov_b32 m0, s28
	s_nop 0
	global_load_lds_dwordx4 v[160:161], off
	s_waitcnt vmcnt(8)
	s_waitcnt lgkmcnt(0)
	s_barrier
	s_setprio 1
	s_waitcnt lgkmcnt(0)
	v_mfma_f32_16x16x32_bf16 v[60:63], v[152:155], v[198:201], v[60:63]
	v_mfma_f32_16x16x32_bf16 v[56:59], v[172:175], v[198:201], v[56:59]
	v_mfma_f32_16x16x32_bf16 v[44:47], v[152:155], v[206:209], v[44:47]
	v_mfma_f32_16x16x32_bf16 v[40:43], v[172:175], v[206:209], v[40:43]
	v_mfma_f32_16x16x32_bf16 v[28:31], v[152:155], v[214:217], v[28:31]
	v_mfma_f32_16x16x32_bf16 v[24:27], v[172:175], v[214:217], v[24:27]
	v_mfma_f32_16x16x32_bf16 v[12:15], v[152:155], v[228:231], v[12:15]
	v_mfma_f32_16x16x32_bf16 v[8:11], v[172:175], v[228:231], v[8:11]
	v_mfma_f32_16x16x32_bf16 v[60:63], v[156:159], v[202:205], v[60:63]
	v_mfma_f32_16x16x32_bf16 v[56:59], v[176:179], v[202:205], v[56:59]
	v_mfma_f32_16x16x32_bf16 v[44:47], v[156:159], v[210:213], v[44:47]
	v_mfma_f32_16x16x32_bf16 v[40:43], v[176:179], v[210:213], v[40:43]
	v_mfma_f32_16x16x32_bf16 v[28:31], v[156:159], v[224:227], v[28:31]
	v_mfma_f32_16x16x32_bf16 v[24:27], v[176:179], v[224:227], v[24:27]
	v_mfma_f32_16x16x32_bf16 v[12:15], v[156:159], v[232:235], v[12:15]
	v_mfma_f32_16x16x32_bf16 v[8:11], v[176:179], v[232:235], v[8:11]
	s_setprio 0
	s_setprio 1
	v_mfma_f32_16x16x32_bf16 v[52:55], v[180:183], v[198:201], v[52:55]
	v_mfma_f32_16x16x32_bf16 v[48:51], v[190:193], v[198:201], v[48:51]
	v_mfma_f32_16x16x32_bf16 v[36:39], v[180:183], v[206:209], v[36:39]
	v_mfma_f32_16x16x32_bf16 v[32:35], v[190:193], v[206:209], v[32:35]
	v_mfma_f32_16x16x32_bf16 v[20:23], v[180:183], v[214:217], v[20:23]
	v_mfma_f32_16x16x32_bf16 v[16:19], v[190:193], v[214:217], v[16:19]
	v_mfma_f32_16x16x32_bf16 v[4:7], v[180:183], v[228:231], v[4:7]
	v_mfma_f32_16x16x32_bf16 v[0:3], v[190:193], v[228:231], v[0:3]
	v_mfma_f32_16x16x32_bf16 v[52:55], v[186:189], v[202:205], v[52:55]
	v_mfma_f32_16x16x32_bf16 v[48:51], v[194:197], v[202:205], v[48:51]
	v_mfma_f32_16x16x32_bf16 v[36:39], v[186:189], v[210:213], v[36:39]
	v_mfma_f32_16x16x32_bf16 v[32:35], v[194:197], v[210:213], v[32:35]
	v_mfma_f32_16x16x32_bf16 v[20:23], v[186:189], v[224:227], v[20:23]
	v_mfma_f32_16x16x32_bf16 v[16:19], v[194:197], v[224:227], v[16:19]
	v_mfma_f32_16x16x32_bf16 v[4:7], v[186:189], v[232:235], v[4:7]
	v_mfma_f32_16x16x32_bf16 v[0:3], v[194:197], v[232:235], v[0:3]
	s_add_u32 s6, s6, 0x100
	s_addc_u32 s7, s7, 0
	s_add_u32 s10, s10, 0x100
	s_addc_u32 s11, s11, 0
	s_cmp_ge_i32 s12, s36
	s_mov_b32 s8, s12
	s_setprio 0
	s_barrier
	s_cbranch_scc0 .LBB0_207

.LBB0_642:
	ds_read_b128 v[146:149], v153
	ds_read_b128 v[156:159], v153 offset:1024
	ds_read_b128 v[160:163], v153 offset:2048
	ds_read_b128 v[164:167], v153 offset:3072
	ds_read_b128 v[168:171], v154
	ds_read_b128 v[172:175], v154 offset:1024
	ds_read_b128 v[176:179], v154 offset:2048
	ds_read_b128 v[180:183], v154 offset:3072
	s_add_i32 s64, s58, 2
	s_add_u32 s65, s56, 0x80
	s_addc_u32 s59, s57, 0
	s_cmp_eq_u32 s49, s58
	s_cselect_b32 s58, s8, s65
	s_cselect_b32 s59, s9, s59
	s_cselect_b32 s67, s43, s63
	s_cselect_b32 s66, s42, s62
	v_lshl_add_u64 v[224:225], s[56:57], 0, v[138:139]
	s_add_i32 m0, s3, 0xc000
	ds_read_b128 v[186:189], v155
	ds_read_b128 v[190:193], v155 offset:1024
	ds_read_b128 v[194:197], v155 offset:2048
	ds_read_b128 v[198:201], v155 offset:3072
	ds_read_b128 v[202:205], v155 offset:4096
	ds_read_b128 v[206:209], v155 offset:5120
	ds_read_b128 v[210:213], v155 offset:6144
	ds_read_b128 v[214:217], v155 offset:7168
	global_load_lds_dwordx4 v[224:225], off
	v_lshl_add_u64 v[224:225], s[56:57], 0, v[140:141]
	s_add_i32 m0, s3, 0xe000
	s_nop 0
	global_load_lds_dwordx4 v[224:225], off
	s_waitcnt vmcnt(8)
	s_waitcnt lgkmcnt(0)
	s_barrier
	s_setprio 1
	s_waitcnt lgkmcnt(0)
	v_mfma_f32_16x16x32_bf16 v[124:127], v[146:149], v[186:189], v[124:127]
	v_mfma_f32_16x16x32_bf16 v[120:123], v[160:163], v[186:189], v[120:123]
	v_mfma_f32_16x16x32_bf16 v[108:111], v[146:149], v[194:197], v[108:111]
	v_mfma_f32_16x16x32_bf16 v[104:107], v[160:163], v[194:197], v[104:107]
	v_mfma_f32_16x16x32_bf16 v[92:95], v[146:149], v[202:205], v[92:95]
	v_mfma_f32_16x16x32_bf16 v[88:91], v[160:163], v[202:205], v[88:91]
	v_mfma_f32_16x16x32_bf16 v[76:79], v[146:149], v[210:213], v[76:79]
	v_mfma_f32_16x16x32_bf16 v[72:75], v[160:163], v[210:213], v[72:75]
	v_mfma_f32_16x16x32_bf16 v[124:127], v[156:159], v[190:193], v[124:127]
	v_mfma_f32_16x16x32_bf16 v[120:123], v[164:167], v[190:193], v[120:123]
	v_mfma_f32_16x16x32_bf16 v[108:111], v[156:159], v[198:201], v[108:111]
	v_mfma_f32_16x16x32_bf16 v[104:107], v[164:167], v[198:201], v[104:107]
	v_mfma_f32_16x16x32_bf16 v[92:95], v[156:159], v[206:209], v[92:95]
	v_mfma_f32_16x16x32_bf16 v[88:91], v[164:167], v[206:209], v[88:91]
	v_mfma_f32_16x16x32_bf16 v[76:79], v[156:159], v[214:217], v[76:79]
	v_mfma_f32_16x16x32_bf16 v[72:75], v[164:167], v[214:217], v[72:75]
	s_setprio 0
	s_setprio 1
	v_mfma_f32_16x16x32_bf16 v[116:119], v[168:171], v[186:189], v[116:119]
	v_mfma_f32_16x16x32_bf16 v[112:115], v[176:179], v[186:189], v[112:115]
	v_mfma_f32_16x16x32_bf16 v[100:103], v[168:171], v[194:197], v[100:103]
	v_mfma_f32_16x16x32_bf16 v[96:99], v[176:179], v[194:197], v[96:99]
	v_mfma_f32_16x16x32_bf16 v[84:87], v[168:171], v[202:205], v[84:87]
	v_mfma_f32_16x16x32_bf16 v[80:83], v[176:179], v[202:205], v[80:83]
	v_mfma_f32_16x16x32_bf16 v[68:71], v[168:171], v[210:213], v[68:71]
	v_mfma_f32_16x16x32_bf16 v[64:67], v[176:179], v[210:213], v[64:67]
	v_mfma_f32_16x16x32_bf16 v[116:119], v[172:175], v[190:193], v[116:119]
	v_mfma_f32_16x16x32_bf16 v[112:115], v[180:183], v[190:193], v[112:115]
	v_mfma_f32_16x16x32_bf16 v[100:103], v[172:175], v[198:201], v[100:103]
	v_mfma_f32_16x16x32_bf16 v[96:99], v[180:183], v[198:201], v[96:99]
	v_mfma_f32_16x16x32_bf16 v[84:87], v[172:175], v[206:209], v[84:87]
	v_mfma_f32_16x16x32_bf16 v[80:83], v[180:183], v[206:209], v[80:83]
	v_mfma_f32_16x16x32_bf16 v[68:71], v[172:175], v[214:217], v[68:71]
	v_mfma_f32_16x16x32_bf16 v[64:67], v[180:183], v[214:217], v[64:67]
	s_setprio 0
	s_barrier
	s_add_i32 s65, s50, s31
	v_lshl_add_u64 v[224:225], s[66:67], 0, v[130:131]
	s_mov_b32 m0, s65
	ds_read_b128 v[186:189], v155 offset:16384
	ds_read_b128 v[190:193], v155 offset:17408
	ds_read_b128 v[194:197], v155 offset:18432
	ds_read_b128 v[198:201], v155 offset:19456
	ds_read_b128 v[202:205], v155 offset:20480
	ds_read_b128 v[206:209], v155 offset:21504
	ds_read_b128 v[210:213], v155 offset:22528
	ds_read_b128 v[214:217], v155 offset:23552
	global_load_lds_dwordx4 v[224:225], off
	s_add_i32 m0, s65, 0x2000
	v_lshl_add_u64 v[226:227], s[66:67], 0, v[134:135]
	s_add_u32 s66, s66, s18
	s_addc_u32 s67, s67, s19
	s_add_i32 s65, s51, s31
	global_load_lds_dwordx4 v[226:227], off
	v_lshl_add_u64 v[228:229], s[66:67], 0, v[130:131]
	s_mov_b32 m0, s65
	v_lshl_add_u64 v[230:231], s[66:67], 0, v[134:135]
	global_load_lds_dwordx4 v[228:229], off
	s_add_i32 m0, s65, 0x2000
	v_lshl_add_u64 v[232:233], s[58:59], 0, v[128:129]
	global_load_lds_dwordx4 v[230:231], off
	s_mov_b32 m0, s3
	v_lshl_add_u64 v[234:235], s[58:59], 0, v[132:133]
	global_load_lds_dwordx4 v[232:233], off
	s_mov_b32 m0, s28
	s_nop 0
	global_load_lds_dwordx4 v[234:235], off
	s_waitcnt vmcnt(8)
	s_waitcnt lgkmcnt(0)
	s_barrier
	s_setprio 1
	s_waitcnt lgkmcnt(0)
	v_mfma_f32_16x16x32_bf16 v[60:63], v[146:149], v[186:189], v[60:63]
	v_mfma_f32_16x16x32_bf16 v[56:59], v[160:163], v[186:189], v[56:59]
	v_mfma_f32_16x16x32_bf16 v[44:47], v[146:149], v[194:197], v[44:47]
	v_mfma_f32_16x16x32_bf16 v[40:43], v[160:163], v[194:197], v[40:43]
	v_mfma_f32_16x16x32_bf16 v[28:31], v[146:149], v[202:205], v[28:31]
	v_mfma_f32_16x16x32_bf16 v[24:27], v[160:163], v[202:205], v[24:27]
	v_mfma_f32_16x16x32_bf16 v[12:15], v[146:149], v[210:213], v[12:15]
	v_mfma_f32_16x16x32_bf16 v[8:11], v[160:163], v[210:213], v[8:11]
	v_mfma_f32_16x16x32_bf16 v[60:63], v[156:159], v[190:193], v[60:63]
	v_mfma_f32_16x16x32_bf16 v[56:59], v[164:167], v[190:193], v[56:59]
	v_mfma_f32_16x16x32_bf16 v[44:47], v[156:159], v[198:201], v[44:47]
	v_mfma_f32_16x16x32_bf16 v[40:43], v[164:167], v[198:201], v[40:43]
	v_mfma_f32_16x16x32_bf16 v[28:31], v[156:159], v[206:209], v[28:31]
	v_mfma_f32_16x16x32_bf16 v[24:27], v[164:167], v[206:209], v[24:27]
	v_mfma_f32_16x16x32_bf16 v[12:15], v[156:159], v[214:217], v[12:15]
	v_mfma_f32_16x16x32_bf16 v[8:11], v[164:167], v[214:217], v[8:11]
	s_setprio 0
	s_setprio 1
	v_mfma_f32_16x16x32_bf16 v[52:55], v[168:171], v[186:189], v[52:55]
	v_mfma_f32_16x16x32_bf16 v[48:51], v[176:179], v[186:189], v[48:51]
	v_mfma_f32_16x16x32_bf16 v[36:39], v[168:171], v[194:197], v[36:39]
	v_mfma_f32_16x16x32_bf16 v[32:35], v[176:179], v[194:197], v[32:35]
	v_mfma_f32_16x16x32_bf16 v[20:23], v[168:171], v[202:205], v[20:23]
	v_mfma_f32_16x16x32_bf16 v[16:19], v[176:179], v[202:205], v[16:19]
	v_mfma_f32_16x16x32_bf16 v[4:7], v[168:171], v[210:213], v[4:7]
	v_mfma_f32_16x16x32_bf16 v[0:3], v[176:179], v[210:213], v[0:3]
	v_mfma_f32_16x16x32_bf16 v[52:55], v[172:175], v[190:193], v[52:55]
	v_mfma_f32_16x16x32_bf16 v[48:51], v[180:183], v[190:193], v[48:51]
	v_mfma_f32_16x16x32_bf16 v[36:39], v[172:175], v[198:201], v[36:39]
	v_mfma_f32_16x16x32_bf16 v[32:35], v[180:183], v[198:201], v[32:35]
	v_mfma_f32_16x16x32_bf16 v[20:23], v[172:175], v[206:209], v[20:23]
	v_mfma_f32_16x16x32_bf16 v[16:19], v[180:183], v[206:209], v[16:19]
	v_mfma_f32_16x16x32_bf16 v[4:7], v[172:175], v[214:217], v[4:7]
	v_mfma_f32_16x16x32_bf16 v[0:3], v[180:183], v[214:217], v[0:3]
	s_setprio 0
	s_barrier
	s_add_i32 s65, 0, 0x18000
	v_add_u32_e32 v136, s65, v151
	s_add_i32 s66, 0, 0x1c000
	ds_read_b128 v[146:149], v136
	ds_read_b128 v[156:159], v136 offset:1024
	ds_read_b128 v[160:163], v136 offset:2048
	ds_read_b128 v[164:167], v136 offset:3072
	v_add_u32_e32 v136, s66, v151
	ds_read_b128 v[168:171], v136
	ds_read_b128 v[172:175], v136 offset:1024
	ds_read_b128 v[176:179], v136 offset:2048
	ds_read_b128 v[180:183], v136 offset:3072
	s_add_u32 s58, s58, s18
	s_addc_u32 s59, s59, s19
	s_mov_b32 m0, s33
	v_lshl_add_u64 v[236:237], s[58:59], 0, v[128:129]
	ds_read_b128 v[186:189], v155 offset:32768
	ds_read_b128 v[190:193], v155 offset:33792
	ds_read_b128 v[194:197], v155 offset:34816
	ds_read_b128 v[198:201], v155 offset:35840
	ds_read_b128 v[202:205], v155 offset:36864
	ds_read_b128 v[206:209], v155 offset:37888
	ds_read_b128 v[210:213], v155 offset:38912
	ds_read_b128 v[214:217], v155 offset:39936
	global_load_lds_dwordx4 v[236:237], off
	v_lshl_add_u64 v[236:237], s[58:59], 0, v[132:133]
	s_mov_b32 m0, s44
	s_nop 0
	global_load_lds_dwordx4 v[236:237], off
	s_waitcnt vmcnt(8)
	s_waitcnt lgkmcnt(0)
	s_barrier
	s_setprio 1
	s_waitcnt lgkmcnt(0)
	v_mfma_f32_16x16x32_bf16 v[124:127], v[146:149], v[186:189], v[124:127]
	v_mfma_f32_16x16x32_bf16 v[120:123], v[160:163], v[186:189], v[120:123]
	v_mfma_f32_16x16x32_bf16 v[108:111], v[146:149], v[194:197], v[108:111]
	v_mfma_f32_16x16x32_bf16 v[104:107], v[160:163], v[194:197], v[104:107]
	v_mfma_f32_16x16x32_bf16 v[92:95], v[146:149], v[202:205], v[92:95]
	v_mfma_f32_16x16x32_bf16 v[88:91], v[160:163], v[202:205], v[88:91]
	v_mfma_f32_16x16x32_bf16 v[76:79], v[146:149], v[210:213], v[76:79]
	v_mfma_f32_16x16x32_bf16 v[72:75], v[160:163], v[210:213], v[72:75]
	v_mfma_f32_16x16x32_bf16 v[124:127], v[156:159], v[190:193], v[124:127]
	v_mfma_f32_16x16x32_bf16 v[120:123], v[164:167], v[190:193], v[120:123]
	v_mfma_f32_16x16x32_bf16 v[108:111], v[156:159], v[198:201], v[108:111]
	v_mfma_f32_16x16x32_bf16 v[104:107], v[164:167], v[198:201], v[104:107]
	v_mfma_f32_16x16x32_bf16 v[92:95], v[156:159], v[206:209], v[92:95]
	v_mfma_f32_16x16x32_bf16 v[88:91], v[164:167], v[206:209], v[88:91]
	v_mfma_f32_16x16x32_bf16 v[76:79], v[156:159], v[214:217], v[76:79]
	v_mfma_f32_16x16x32_bf16 v[72:75], v[164:167], v[214:217], v[72:75]
	s_setprio 0
	s_setprio 1
	v_mfma_f32_16x16x32_bf16 v[116:119], v[168:171], v[186:189], v[116:119]
	v_mfma_f32_16x16x32_bf16 v[112:115], v[176:179], v[186:189], v[112:115]
	v_mfma_f32_16x16x32_bf16 v[100:103], v[168:171], v[194:197], v[100:103]
	v_mfma_f32_16x16x32_bf16 v[96:99], v[176:179], v[194:197], v[96:99]
	v_mfma_f32_16x16x32_bf16 v[84:87], v[168:171], v[202:205], v[84:87]
	v_mfma_f32_16x16x32_bf16 v[80:83], v[176:179], v[202:205], v[80:83]
	v_mfma_f32_16x16x32_bf16 v[68:71], v[168:171], v[210:213], v[68:71]
	v_mfma_f32_16x16x32_bf16 v[64:67], v[176:179], v[210:213], v[64:67]
	v_mfma_f32_16x16x32_bf16 v[116:119], v[172:175], v[190:193], v[116:119]
	v_mfma_f32_16x16x32_bf16 v[112:115], v[180:183], v[190:193], v[112:115]
	v_mfma_f32_16x16x32_bf16 v[100:103], v[172:175], v[198:201], v[100:103]
	v_mfma_f32_16x16x32_bf16 v[96:99], v[180:183], v[198:201], v[96:99]
	v_mfma_f32_16x16x32_bf16 v[84:87], v[172:175], v[206:209], v[84:87]
	v_mfma_f32_16x16x32_bf16 v[80:83], v[180:183], v[206:209], v[80:83]
	v_mfma_f32_16x16x32_bf16 v[68:71], v[172:175], v[214:217], v[68:71]
	v_mfma_f32_16x16x32_bf16 v[64:67], v[180:183], v[214:217], v[64:67]
	s_setprio 0
	s_barrier
	s_add_i32 s58, s65, s31
	v_lshl_add_u64 v[224:225], v[224:225], 0, s[40:41]
	s_mov_b32 m0, s58
	ds_read_b128 v[186:189], v155 offset:49152
	ds_read_b128 v[190:193], v155 offset:50176
	ds_read_b128 v[194:197], v155 offset:51200
	ds_read_b128 v[198:201], v155 offset:52224
	ds_read_b128 v[202:205], v155 offset:53248
	ds_read_b128 v[206:209], v155 offset:54272
	ds_read_b128 v[210:213], v155 offset:55296
	ds_read_b128 v[214:217], v155 offset:56320
	global_load_lds_dwordx4 v[224:225], off
	v_lshl_add_u64 v[224:225], v[226:227], 0, s[40:41]
	s_add_i32 m0, s58, 0x2000
	s_add_i32 s58, s66, s31
	global_load_lds_dwordx4 v[224:225], off
	v_lshl_add_u64 v[224:225], v[228:229], 0, s[40:41]
	s_mov_b32 m0, s58
	s_nop 0
	global_load_lds_dwordx4 v[224:225], off
	v_lshl_add_u64 v[224:225], v[230:231], 0, s[40:41]
	s_add_i32 m0, s58, 0x2000
	s_nop 0
	global_load_lds_dwordx4 v[224:225], off
	v_lshl_add_u64 v[224:225], v[232:233], 0, s[40:41]
	s_mov_b32 m0, s47
	s_nop 0
	global_load_lds_dwordx4 v[224:225], off
	v_lshl_add_u64 v[224:225], v[234:235], 0, s[40:41]
	s_mov_b32 m0, s48
	s_nop 0
	global_load_lds_dwordx4 v[224:225], off
	s_waitcnt vmcnt(8)
	s_waitcnt lgkmcnt(0)
	s_barrier
	s_setprio 1
	s_waitcnt lgkmcnt(0)
	v_mfma_f32_16x16x32_bf16 v[60:63], v[146:149], v[186:189], v[60:63]
	v_mfma_f32_16x16x32_bf16 v[56:59], v[160:163], v[186:189], v[56:59]
	v_mfma_f32_16x16x32_bf16 v[44:47], v[146:149], v[194:197], v[44:47]
	v_mfma_f32_16x16x32_bf16 v[40:43], v[160:163], v[194:197], v[40:43]
	v_mfma_f32_16x16x32_bf16 v[28:31], v[146:149], v[202:205], v[28:31]
	v_mfma_f32_16x16x32_bf16 v[24:27], v[160:163], v[202:205], v[24:27]
	v_mfma_f32_16x16x32_bf16 v[12:15], v[146:149], v[210:213], v[12:15]
	v_mfma_f32_16x16x32_bf16 v[8:11], v[160:163], v[210:213], v[8:11]
	v_mfma_f32_16x16x32_bf16 v[60:63], v[156:159], v[190:193], v[60:63]
	v_mfma_f32_16x16x32_bf16 v[56:59], v[164:167], v[190:193], v[56:59]
	v_mfma_f32_16x16x32_bf16 v[44:47], v[156:159], v[198:201], v[44:47]
	v_mfma_f32_16x16x32_bf16 v[40:43], v[164:167], v[198:201], v[40:43]
	v_mfma_f32_16x16x32_bf16 v[28:31], v[156:159], v[206:209], v[28:31]
	v_mfma_f32_16x16x32_bf16 v[24:27], v[164:167], v[206:209], v[24:27]
	v_mfma_f32_16x16x32_bf16 v[12:15], v[156:159], v[214:217], v[12:15]
	v_mfma_f32_16x16x32_bf16 v[8:11], v[164:167], v[214:217], v[8:11]
	s_setprio 0
	s_setprio 1
	v_mfma_f32_16x16x32_bf16 v[52:55], v[168:171], v[186:189], v[52:55]
	v_mfma_f32_16x16x32_bf16 v[48:51], v[176:179], v[186:189], v[48:51]
	v_mfma_f32_16x16x32_bf16 v[36:39], v[168:171], v[194:197], v[36:39]
	v_mfma_f32_16x16x32_bf16 v[32:35], v[176:179], v[194:197], v[32:35]
	v_mfma_f32_16x16x32_bf16 v[20:23], v[168:171], v[202:205], v[20:23]
	v_mfma_f32_16x16x32_bf16 v[16:19], v[176:179], v[202:205], v[16:19]
	v_mfma_f32_16x16x32_bf16 v[4:7], v[168:171], v[210:213], v[4:7]
	v_mfma_f32_16x16x32_bf16 v[0:3], v[176:179], v[210:213], v[0:3]
	v_mfma_f32_16x16x32_bf16 v[52:55], v[172:175], v[190:193], v[52:55]
	v_mfma_f32_16x16x32_bf16 v[48:51], v[180:183], v[190:193], v[48:51]
	v_mfma_f32_16x16x32_bf16 v[36:39], v[172:175], v[198:201], v[36:39]
	v_mfma_f32_16x16x32_bf16 v[32:35], v[180:183], v[198:201], v[32:35]
	v_mfma_f32_16x16x32_bf16 v[20:23], v[172:175], v[206:209], v[20:23]
	v_mfma_f32_16x16x32_bf16 v[16:19], v[180:183], v[206:209], v[16:19]
	v_mfma_f32_16x16x32_bf16 v[4:7], v[172:175], v[214:217], v[4:7]
	v_mfma_f32_16x16x32_bf16 v[0:3], v[180:183], v[214:217], v[0:3]
	s_add_u32 s56, s56, 0x100
	s_addc_u32 s57, s57, 0
	s_add_u32 s62, s62, 0x100
	s_addc_u32 s63, s63, 0
	s_cmp_ge_i32 s64, s45
	s_mov_b32 s58, s64
	s_setprio 0
	s_barrier
	s_cbranch_scc0 .LBB0_642

.LBB0_679:
	ds_read_b128 v[150:153], v147
	ds_read_b128 v[154:157], v147 offset:1024
	ds_read_b128 v[158:161], v147 offset:2048
	ds_read_b128 v[162:165], v147 offset:3072
	ds_read_b128 v[166:169], v148
	ds_read_b128 v[170:173], v148 offset:1024
	ds_read_b128 v[174:177], v148 offset:2048
	ds_read_b128 v[178:181], v148 offset:3072
	s_add_i32 s79, s60, 2
	s_add_u32 s80, s58, 0x80
	s_addc_u32 s61, s59, 0
	s_cmp_eq_u32 s65, s60
	s_cselect_b32 s60, s4, s80
	s_cselect_b32 s61, s5, s61
	s_cselect_b32 s81, s57, s78
	s_cselect_b32 s80, s56, s71
	v_lshl_add_u64 v[182:183], s[58:59], 0, v[136:137]
	s_add_i32 m0, s45, 0xc000
	ds_read_b128 v[186:189], v149
	ds_read_b128 v[190:193], v149 offset:1024
	ds_read_b128 v[194:197], v149 offset:2048
	ds_read_b128 v[198:201], v149 offset:3072
	ds_read_b128 v[202:205], v149 offset:4096
	ds_read_b128 v[206:209], v149 offset:5120
	ds_read_b128 v[210:213], v149 offset:6144
	ds_read_b128 v[214:217], v149 offset:7168
	global_load_lds_dwordx4 v[182:183], off
	v_lshl_add_u64 v[182:183], s[58:59], 0, v[138:139]
	s_add_i32 m0, s45, 0xe000
	s_nop 0
	global_load_lds_dwordx4 v[182:183], off
	s_waitcnt vmcnt(8)
	s_waitcnt lgkmcnt(0)
	s_barrier
	s_setprio 1
	s_waitcnt lgkmcnt(0)
	v_mfma_f32_16x16x32_bf16 v[120:123], v[150:153], v[186:189], v[120:123]
	v_mfma_f32_16x16x32_bf16 v[124:127], v[158:161], v[186:189], v[124:127]
	v_mfma_f32_16x16x32_bf16 v[108:111], v[150:153], v[194:197], v[108:111]
	v_mfma_f32_16x16x32_bf16 v[104:107], v[158:161], v[194:197], v[104:107]
	v_mfma_f32_16x16x32_bf16 v[92:95], v[150:153], v[202:205], v[92:95]
	v_mfma_f32_16x16x32_bf16 v[88:91], v[158:161], v[202:205], v[88:91]
	v_mfma_f32_16x16x32_bf16 v[76:79], v[150:153], v[210:213], v[76:79]
	v_mfma_f32_16x16x32_bf16 v[72:75], v[158:161], v[210:213], v[72:75]
	v_mfma_f32_16x16x32_bf16 v[120:123], v[154:157], v[190:193], v[120:123]
	v_mfma_f32_16x16x32_bf16 v[124:127], v[162:165], v[190:193], v[124:127]
	v_mfma_f32_16x16x32_bf16 v[108:111], v[154:157], v[198:201], v[108:111]
	v_mfma_f32_16x16x32_bf16 v[104:107], v[162:165], v[198:201], v[104:107]
	v_mfma_f32_16x16x32_bf16 v[92:95], v[154:157], v[206:209], v[92:95]
	v_mfma_f32_16x16x32_bf16 v[88:91], v[162:165], v[206:209], v[88:91]
	v_mfma_f32_16x16x32_bf16 v[76:79], v[154:157], v[214:217], v[76:79]
	v_mfma_f32_16x16x32_bf16 v[72:75], v[162:165], v[214:217], v[72:75]
	s_setprio 0
	s_setprio 1
	v_mfma_f32_16x16x32_bf16 v[116:119], v[166:169], v[186:189], v[116:119]
	v_mfma_f32_16x16x32_bf16 v[112:115], v[174:177], v[186:189], v[112:115]
	v_mfma_f32_16x16x32_bf16 v[100:103], v[166:169], v[194:197], v[100:103]
	v_mfma_f32_16x16x32_bf16 v[96:99], v[174:177], v[194:197], v[96:99]
	v_mfma_f32_16x16x32_bf16 v[84:87], v[166:169], v[202:205], v[84:87]
	v_mfma_f32_16x16x32_bf16 v[80:83], v[174:177], v[202:205], v[80:83]
	v_mfma_f32_16x16x32_bf16 v[68:71], v[166:169], v[210:213], v[68:71]
	v_mfma_f32_16x16x32_bf16 v[64:67], v[174:177], v[210:213], v[64:67]
	v_mfma_f32_16x16x32_bf16 v[116:119], v[170:173], v[190:193], v[116:119]
	v_mfma_f32_16x16x32_bf16 v[112:115], v[178:181], v[190:193], v[112:115]
	v_mfma_f32_16x16x32_bf16 v[100:103], v[170:173], v[198:201], v[100:103]
	v_mfma_f32_16x16x32_bf16 v[96:99], v[178:181], v[198:201], v[96:99]
	v_mfma_f32_16x16x32_bf16 v[84:87], v[170:173], v[206:209], v[84:87]
	v_mfma_f32_16x16x32_bf16 v[80:83], v[178:181], v[206:209], v[80:83]
	v_mfma_f32_16x16x32_bf16 v[68:71], v[170:173], v[214:217], v[68:71]
	v_mfma_f32_16x16x32_bf16 v[64:67], v[178:181], v[214:217], v[64:67]
	s_setprio 0
	s_barrier
	s_add_i32 s82, s66, s31
	v_lshl_add_u64 v[182:183], s[80:81], 0, v[132:133]
	s_mov_b32 m0, s82
	ds_read_b128 v[186:189], v149 offset:16384
	ds_read_b128 v[190:193], v149 offset:17408
	ds_read_b128 v[194:197], v149 offset:18432
	ds_read_b128 v[198:201], v149 offset:19456
	ds_read_b128 v[202:205], v149 offset:20480
	ds_read_b128 v[206:209], v149 offset:21504
	ds_read_b128 v[210:213], v149 offset:22528
	ds_read_b128 v[214:217], v149 offset:23552
	global_load_lds_dwordx4 v[182:183], off
	s_add_i32 m0, s82, 0x2000
	v_lshl_add_u64 v[224:225], s[80:81], 0, v[128:129]
	s_add_u32 s80, s80, s36
	s_addc_u32 s81, s81, s37
	s_add_i32 s82, s67, s31
	global_load_lds_dwordx4 v[224:225], off
	v_lshl_add_u64 v[226:227], s[80:81], 0, v[132:133]
	s_mov_b32 m0, s82
	v_lshl_add_u64 v[228:229], s[80:81], 0, v[128:129]
	global_load_lds_dwordx4 v[226:227], off
	s_add_i32 m0, s82, 0x2000
	v_lshl_add_u64 v[230:231], s[60:61], 0, v[134:135]
	global_load_lds_dwordx4 v[228:229], off
	s_mov_b32 m0, s45
	v_lshl_add_u64 v[232:233], s[60:61], 0, v[130:131]
	global_load_lds_dwordx4 v[230:231], off
	s_mov_b32 m0, s46
	s_nop 0
	global_load_lds_dwordx4 v[232:233], off
	s_waitcnt vmcnt(8)
	s_waitcnt lgkmcnt(0)
	s_barrier
	s_setprio 1
	s_waitcnt lgkmcnt(0)
	v_mfma_f32_16x16x32_bf16 v[60:63], v[150:153], v[186:189], v[60:63]
	v_mfma_f32_16x16x32_bf16 v[56:59], v[158:161], v[186:189], v[56:59]
	v_mfma_f32_16x16x32_bf16 v[44:47], v[150:153], v[194:197], v[44:47]
	v_mfma_f32_16x16x32_bf16 v[40:43], v[158:161], v[194:197], v[40:43]
	v_mfma_f32_16x16x32_bf16 v[28:31], v[150:153], v[202:205], v[28:31]
	v_mfma_f32_16x16x32_bf16 v[24:27], v[158:161], v[202:205], v[24:27]
	v_mfma_f32_16x16x32_bf16 v[12:15], v[150:153], v[210:213], v[12:15]
	v_mfma_f32_16x16x32_bf16 v[8:11], v[158:161], v[210:213], v[8:11]
	v_mfma_f32_16x16x32_bf16 v[60:63], v[154:157], v[190:193], v[60:63]
	v_mfma_f32_16x16x32_bf16 v[56:59], v[162:165], v[190:193], v[56:59]
	v_mfma_f32_16x16x32_bf16 v[44:47], v[154:157], v[198:201], v[44:47]
	v_mfma_f32_16x16x32_bf16 v[40:43], v[162:165], v[198:201], v[40:43]
	v_mfma_f32_16x16x32_bf16 v[28:31], v[154:157], v[206:209], v[28:31]
	v_mfma_f32_16x16x32_bf16 v[24:27], v[162:165], v[206:209], v[24:27]
	v_mfma_f32_16x16x32_bf16 v[12:15], v[154:157], v[214:217], v[12:15]
	v_mfma_f32_16x16x32_bf16 v[8:11], v[162:165], v[214:217], v[8:11]
	s_setprio 0
	s_setprio 1
	v_mfma_f32_16x16x32_bf16 v[52:55], v[166:169], v[186:189], v[52:55]
	v_mfma_f32_16x16x32_bf16 v[48:51], v[174:177], v[186:189], v[48:51]
	v_mfma_f32_16x16x32_bf16 v[36:39], v[166:169], v[194:197], v[36:39]
	v_mfma_f32_16x16x32_bf16 v[32:35], v[174:177], v[194:197], v[32:35]
	v_mfma_f32_16x16x32_bf16 v[20:23], v[166:169], v[202:205], v[20:23]
	v_mfma_f32_16x16x32_bf16 v[16:19], v[174:177], v[202:205], v[16:19]
	v_mfma_f32_16x16x32_bf16 v[4:7], v[166:169], v[210:213], v[4:7]
	v_mfma_f32_16x16x32_bf16 v[0:3], v[174:177], v[210:213], v[0:3]
	v_mfma_f32_16x16x32_bf16 v[52:55], v[170:173], v[190:193], v[52:55]
	v_mfma_f32_16x16x32_bf16 v[48:51], v[178:181], v[190:193], v[48:51]
	v_mfma_f32_16x16x32_bf16 v[36:39], v[170:173], v[198:201], v[36:39]
	v_mfma_f32_16x16x32_bf16 v[32:35], v[178:181], v[198:201], v[32:35]
	v_mfma_f32_16x16x32_bf16 v[20:23], v[170:173], v[206:209], v[20:23]
	v_mfma_f32_16x16x32_bf16 v[16:19], v[178:181], v[206:209], v[16:19]
	v_mfma_f32_16x16x32_bf16 v[4:7], v[170:173], v[214:217], v[4:7]
	v_mfma_f32_16x16x32_bf16 v[0:3], v[178:181], v[214:217], v[0:3]
	s_setprio 0
	s_barrier
	s_add_i32 s80, 0, 0x18000
	s_add_i32 s81, 0, 0x1c000
	v_add_u32_e32 v162, s80, v145
	v_add_u32_e32 v178, s81, v145
	ds_read_b128 v[150:153], v162
	ds_read_b128 v[154:157], v162 offset:1024
	ds_read_b128 v[158:161], v162 offset:2048
	ds_read_b128 v[162:165], v162 offset:3072
	ds_read_b128 v[166:169], v178
	ds_read_b128 v[170:173], v178 offset:1024
	ds_read_b128 v[174:177], v178 offset:2048
	ds_read_b128 v[178:181], v178 offset:3072
	s_add_u32 s60, s60, s36
	s_addc_u32 s61, s61, s37
	s_mov_b32 m0, s47
	v_lshl_add_u64 v[234:235], s[60:61], 0, v[134:135]
	ds_read_b128 v[186:189], v149 offset:32768
	ds_read_b128 v[190:193], v149 offset:33792
	ds_read_b128 v[194:197], v149 offset:34816
	ds_read_b128 v[198:201], v149 offset:35840
	ds_read_b128 v[202:205], v149 offset:36864
	ds_read_b128 v[206:209], v149 offset:37888
	ds_read_b128 v[210:213], v149 offset:38912
	ds_read_b128 v[214:217], v149 offset:39936
	global_load_lds_dwordx4 v[234:235], off
	v_lshl_add_u64 v[234:235], s[60:61], 0, v[130:131]
	s_mov_b32 m0, s48
	s_nop 0
	global_load_lds_dwordx4 v[234:235], off
	s_waitcnt vmcnt(8)
	s_waitcnt lgkmcnt(0)
	s_barrier
	s_setprio 1
	s_waitcnt lgkmcnt(0)
	v_mfma_f32_16x16x32_bf16 v[120:123], v[150:153], v[186:189], v[120:123]
	v_mfma_f32_16x16x32_bf16 v[124:127], v[158:161], v[186:189], v[124:127]
	v_mfma_f32_16x16x32_bf16 v[108:111], v[150:153], v[194:197], v[108:111]
	v_mfma_f32_16x16x32_bf16 v[104:107], v[158:161], v[194:197], v[104:107]
	v_mfma_f32_16x16x32_bf16 v[92:95], v[150:153], v[202:205], v[92:95]
	v_mfma_f32_16x16x32_bf16 v[88:91], v[158:161], v[202:205], v[88:91]
	v_mfma_f32_16x16x32_bf16 v[76:79], v[150:153], v[210:213], v[76:79]
	v_mfma_f32_16x16x32_bf16 v[72:75], v[158:161], v[210:213], v[72:75]
	v_mfma_f32_16x16x32_bf16 v[120:123], v[154:157], v[190:193], v[120:123]
	v_mfma_f32_16x16x32_bf16 v[124:127], v[162:165], v[190:193], v[124:127]
	v_mfma_f32_16x16x32_bf16 v[108:111], v[154:157], v[198:201], v[108:111]
	v_mfma_f32_16x16x32_bf16 v[104:107], v[162:165], v[198:201], v[104:107]
	v_mfma_f32_16x16x32_bf16 v[92:95], v[154:157], v[206:209], v[92:95]
	v_mfma_f32_16x16x32_bf16 v[88:91], v[162:165], v[206:209], v[88:91]
	v_mfma_f32_16x16x32_bf16 v[76:79], v[154:157], v[214:217], v[76:79]
	v_mfma_f32_16x16x32_bf16 v[72:75], v[162:165], v[214:217], v[72:75]
	s_setprio 0
	s_setprio 1
	v_mfma_f32_16x16x32_bf16 v[116:119], v[166:169], v[186:189], v[116:119]
	v_mfma_f32_16x16x32_bf16 v[112:115], v[174:177], v[186:189], v[112:115]
	v_mfma_f32_16x16x32_bf16 v[100:103], v[166:169], v[194:197], v[100:103]
	v_mfma_f32_16x16x32_bf16 v[96:99], v[174:177], v[194:197], v[96:99]
	v_mfma_f32_16x16x32_bf16 v[84:87], v[166:169], v[202:205], v[84:87]
	v_mfma_f32_16x16x32_bf16 v[80:83], v[174:177], v[202:205], v[80:83]
	v_mfma_f32_16x16x32_bf16 v[68:71], v[166:169], v[210:213], v[68:71]
	v_mfma_f32_16x16x32_bf16 v[64:67], v[174:177], v[210:213], v[64:67]
	v_mfma_f32_16x16x32_bf16 v[116:119], v[170:173], v[190:193], v[116:119]
	v_mfma_f32_16x16x32_bf16 v[112:115], v[178:181], v[190:193], v[112:115]
	v_mfma_f32_16x16x32_bf16 v[100:103], v[170:173], v[198:201], v[100:103]
	v_mfma_f32_16x16x32_bf16 v[96:99], v[178:181], v[198:201], v[96:99]
	v_mfma_f32_16x16x32_bf16 v[84:87], v[170:173], v[206:209], v[84:87]
	v_mfma_f32_16x16x32_bf16 v[80:83], v[178:181], v[206:209], v[80:83]
	v_mfma_f32_16x16x32_bf16 v[68:71], v[170:173], v[214:217], v[68:71]
	v_mfma_f32_16x16x32_bf16 v[64:67], v[178:181], v[214:217], v[64:67]
	s_setprio 0
	s_barrier
	s_add_i32 s60, s80, s31
	v_lshl_add_u64 v[182:183], v[182:183], 0, s[40:41]
	s_mov_b32 m0, s60
	ds_read_b128 v[186:189], v149 offset:49152
	ds_read_b128 v[190:193], v149 offset:50176
	ds_read_b128 v[194:197], v149 offset:51200
	ds_read_b128 v[198:201], v149 offset:52224
	ds_read_b128 v[202:205], v149 offset:53248
	ds_read_b128 v[206:209], v149 offset:54272
	ds_read_b128 v[210:213], v149 offset:55296
	ds_read_b128 v[214:217], v149 offset:56320
	global_load_lds_dwordx4 v[182:183], off
	v_lshl_add_u64 v[182:183], v[224:225], 0, s[40:41]
	s_add_i32 m0, s60, 0x2000
	s_add_i32 s60, s81, s31
	global_load_lds_dwordx4 v[182:183], off
	v_lshl_add_u64 v[182:183], v[226:227], 0, s[40:41]
	s_mov_b32 m0, s60
	s_nop 0
	global_load_lds_dwordx4 v[182:183], off
	v_lshl_add_u64 v[182:183], v[228:229], 0, s[40:41]
	s_add_i32 m0, s60, 0x2000
	s_nop 0
	global_load_lds_dwordx4 v[182:183], off
	v_lshl_add_u64 v[182:183], v[230:231], 0, s[40:41]
	s_mov_b32 m0, s53
	s_nop 0
	global_load_lds_dwordx4 v[182:183], off
	v_lshl_add_u64 v[182:183], v[232:233], 0, s[40:41]
	s_mov_b32 m0, s64
	s_nop 0
	global_load_lds_dwordx4 v[182:183], off
	s_waitcnt vmcnt(8)
	s_waitcnt lgkmcnt(0)
	s_barrier
	s_setprio 1
	s_waitcnt lgkmcnt(0)
	v_mfma_f32_16x16x32_bf16 v[60:63], v[150:153], v[186:189], v[60:63]
	v_mfma_f32_16x16x32_bf16 v[56:59], v[158:161], v[186:189], v[56:59]
	v_mfma_f32_16x16x32_bf16 v[44:47], v[150:153], v[194:197], v[44:47]
	v_mfma_f32_16x16x32_bf16 v[40:43], v[158:161], v[194:197], v[40:43]
	v_mfma_f32_16x16x32_bf16 v[28:31], v[150:153], v[202:205], v[28:31]
	v_mfma_f32_16x16x32_bf16 v[24:27], v[158:161], v[202:205], v[24:27]
	v_mfma_f32_16x16x32_bf16 v[12:15], v[150:153], v[210:213], v[12:15]
	v_mfma_f32_16x16x32_bf16 v[8:11], v[158:161], v[210:213], v[8:11]
	v_mfma_f32_16x16x32_bf16 v[60:63], v[154:157], v[190:193], v[60:63]
	v_mfma_f32_16x16x32_bf16 v[56:59], v[162:165], v[190:193], v[56:59]
	v_mfma_f32_16x16x32_bf16 v[44:47], v[154:157], v[198:201], v[44:47]
	v_mfma_f32_16x16x32_bf16 v[40:43], v[162:165], v[198:201], v[40:43]
	v_mfma_f32_16x16x32_bf16 v[28:31], v[154:157], v[206:209], v[28:31]
	v_mfma_f32_16x16x32_bf16 v[24:27], v[162:165], v[206:209], v[24:27]
	v_mfma_f32_16x16x32_bf16 v[12:15], v[154:157], v[214:217], v[12:15]
	v_mfma_f32_16x16x32_bf16 v[8:11], v[162:165], v[214:217], v[8:11]
	s_setprio 0
	s_setprio 1
	v_mfma_f32_16x16x32_bf16 v[52:55], v[166:169], v[186:189], v[52:55]
	v_mfma_f32_16x16x32_bf16 v[48:51], v[174:177], v[186:189], v[48:51]
	v_mfma_f32_16x16x32_bf16 v[36:39], v[166:169], v[194:197], v[36:39]
	v_mfma_f32_16x16x32_bf16 v[32:35], v[174:177], v[194:197], v[32:35]
	v_mfma_f32_16x16x32_bf16 v[20:23], v[166:169], v[202:205], v[20:23]
	v_mfma_f32_16x16x32_bf16 v[16:19], v[174:177], v[202:205], v[16:19]
	v_mfma_f32_16x16x32_bf16 v[4:7], v[166:169], v[210:213], v[4:7]
	v_mfma_f32_16x16x32_bf16 v[0:3], v[174:177], v[210:213], v[0:3]
	v_mfma_f32_16x16x32_bf16 v[52:55], v[170:173], v[190:193], v[52:55]
	v_mfma_f32_16x16x32_bf16 v[48:51], v[178:181], v[190:193], v[48:51]
	v_mfma_f32_16x16x32_bf16 v[36:39], v[170:173], v[198:201], v[36:39]
	v_mfma_f32_16x16x32_bf16 v[32:35], v[178:181], v[198:201], v[32:35]
	v_mfma_f32_16x16x32_bf16 v[20:23], v[170:173], v[206:209], v[20:23]
	v_mfma_f32_16x16x32_bf16 v[16:19], v[178:181], v[206:209], v[16:19]
	v_mfma_f32_16x16x32_bf16 v[4:7], v[170:173], v[214:217], v[4:7]
	v_mfma_f32_16x16x32_bf16 v[0:3], v[178:181], v[214:217], v[0:3]
	s_add_u32 s58, s58, 0x100
	s_addc_u32 s59, s59, 0
	s_add_u32 s71, s71, 0x100
	s_addc_u32 s78, s78, 0
	s_cmp_ge_i32 s79, s49
	s_mov_b32 s60, s79
	s_setprio 0
	s_barrier
	s_cbranch_scc0 .LBB0_679
	v_readlane_b32 s82, v248, 38
	v_readlane_b32 s83, v248, 39

.LBB0_921:
	ds_read_b128 v[144:147], v153
	ds_read_b128 v[158:161], v153 offset:1024
	ds_read_b128 v[162:165], v153 offset:2048
	ds_read_b128 v[166:169], v153 offset:3072
	ds_read_b128 v[170:173], v154
	ds_read_b128 v[174:177], v154 offset:1024
	ds_read_b128 v[178:181], v154 offset:2048
	ds_read_b128 v[186:189], v154 offset:3072
	s_add_i32 s63, s42, 2
	s_add_u32 s64, s40, 0x80
	s_addc_u32 s43, s41, 0
	s_cmp_eq_u32 s50, s42
	s_cselect_b32 s42, s6, s64
	s_cselect_b32 s43, s7, s43
	s_cselect_b32 s65, s39, s62
	s_cselect_b32 s64, s38, s61
	s_mov_b32 m0, s53
	v_lshl_add_u64 v[148:149], s[40:41], 0, v[136:137]
	ds_read_b128 v[190:193], v155
	ds_read_b128 v[194:197], v155 offset:1024
	ds_read_b128 v[198:201], v155 offset:2048
	ds_read_b128 v[202:205], v155 offset:3072
	ds_read_b128 v[206:209], v155 offset:4096
	ds_read_b128 v[210:213], v155 offset:5120
	ds_read_b128 v[214:217], v155 offset:6144
	ds_read_b128 v[224:227], v155 offset:7168
	global_load_lds_dwordx4 v[148:149], off
	v_lshl_add_u64 v[148:149], s[40:41], 0, v[138:139]
	s_mov_b32 m0, s54
	s_nop 0
	global_load_lds_dwordx4 v[148:149], off
	s_waitcnt vmcnt(8)
	s_waitcnt lgkmcnt(0)
	s_barrier
	s_setprio 1
	s_waitcnt lgkmcnt(0)
	v_mfma_f32_16x16x32_bf16 v[120:123], v[144:147], v[190:193], v[120:123]
	v_mfma_f32_16x16x32_bf16 v[116:119], v[162:165], v[190:193], v[116:119]
	v_mfma_f32_16x16x32_bf16 v[108:111], v[144:147], v[198:201], v[108:111]
	v_mfma_f32_16x16x32_bf16 v[100:103], v[162:165], v[198:201], v[100:103]
	v_mfma_f32_16x16x32_bf16 v[92:95], v[144:147], v[206:209], v[92:95]
	v_mfma_f32_16x16x32_bf16 v[84:87], v[162:165], v[206:209], v[84:87]
	v_mfma_f32_16x16x32_bf16 v[76:79], v[144:147], v[214:217], v[76:79]
	v_mfma_f32_16x16x32_bf16 v[68:71], v[162:165], v[214:217], v[68:71]
	v_mfma_f32_16x16x32_bf16 v[120:123], v[158:161], v[194:197], v[120:123]
	v_mfma_f32_16x16x32_bf16 v[116:119], v[166:169], v[194:197], v[116:119]
	v_mfma_f32_16x16x32_bf16 v[108:111], v[158:161], v[202:205], v[108:111]
	v_mfma_f32_16x16x32_bf16 v[100:103], v[166:169], v[202:205], v[100:103]
	v_mfma_f32_16x16x32_bf16 v[92:95], v[158:161], v[210:213], v[92:95]
	v_mfma_f32_16x16x32_bf16 v[84:87], v[166:169], v[210:213], v[84:87]
	v_mfma_f32_16x16x32_bf16 v[76:79], v[158:161], v[224:227], v[76:79]
	v_mfma_f32_16x16x32_bf16 v[68:71], v[166:169], v[224:227], v[68:71]
	s_setprio 0
	s_setprio 1
	v_mfma_f32_16x16x32_bf16 v[124:127], v[170:173], v[190:193], v[124:127]
	v_mfma_f32_16x16x32_bf16 v[112:115], v[178:181], v[190:193], v[112:115]
	v_mfma_f32_16x16x32_bf16 v[104:107], v[170:173], v[198:201], v[104:107]
	v_mfma_f32_16x16x32_bf16 v[96:99], v[178:181], v[198:201], v[96:99]
	v_mfma_f32_16x16x32_bf16 v[88:91], v[170:173], v[206:209], v[88:91]
	v_mfma_f32_16x16x32_bf16 v[80:83], v[178:181], v[206:209], v[80:83]
	v_mfma_f32_16x16x32_bf16 v[72:75], v[170:173], v[214:217], v[72:75]
	v_mfma_f32_16x16x32_bf16 v[64:67], v[178:181], v[214:217], v[64:67]
	v_mfma_f32_16x16x32_bf16 v[124:127], v[174:177], v[194:197], v[124:127]
	v_mfma_f32_16x16x32_bf16 v[112:115], v[186:189], v[194:197], v[112:115]
	v_mfma_f32_16x16x32_bf16 v[104:107], v[174:177], v[202:205], v[104:107]
	v_mfma_f32_16x16x32_bf16 v[96:99], v[186:189], v[202:205], v[96:99]
	v_mfma_f32_16x16x32_bf16 v[88:91], v[174:177], v[210:213], v[88:91]
	v_mfma_f32_16x16x32_bf16 v[80:83], v[186:189], v[210:213], v[80:83]
	v_mfma_f32_16x16x32_bf16 v[72:75], v[174:177], v[224:227], v[72:75]
	v_mfma_f32_16x16x32_bf16 v[64:67], v[186:189], v[224:227], v[64:67]
	s_setprio 0
	s_barrier
	s_mov_b32 m0, s55
	v_lshl_add_u64 v[148:149], s[64:65], 0, v[132:133]
	v_lshl_add_u64 v[182:183], s[64:65], 0, v[128:129]
	s_add_u32 s64, s64, s16
	ds_read_b128 v[190:193], v155 offset:16384
	ds_read_b128 v[194:197], v155 offset:17408
	ds_read_b128 v[198:201], v155 offset:18432
	ds_read_b128 v[202:205], v155 offset:19456
	ds_read_b128 v[206:209], v155 offset:20480
	ds_read_b128 v[210:213], v155 offset:21504
	ds_read_b128 v[214:217], v155 offset:22528
	ds_read_b128 v[224:227], v155 offset:23552
	global_load_lds_dwordx4 v[148:149], off
	s_mov_b32 m0, s56
	s_addc_u32 s65, s65, s17
	s_add_i32 s66, s51, s31
	global_load_lds_dwordx4 v[182:183], off
	v_lshl_add_u64 v[228:229], s[64:65], 0, v[132:133]
	s_mov_b32 m0, s66
	v_lshl_add_u64 v[230:231], s[64:65], 0, v[128:129]
	global_load_lds_dwordx4 v[228:229], off
	s_add_i32 m0, s66, 0x2000
	v_lshl_add_u64 v[232:233], s[42:43], 0, v[134:135]
	global_load_lds_dwordx4 v[230:231], off
	s_mov_b32 m0, s28
	v_lshl_add_u64 v[234:235], s[42:43], 0, v[130:131]
	global_load_lds_dwordx4 v[232:233], off
	s_mov_b32 m0, s33
	s_nop 0
	global_load_lds_dwordx4 v[234:235], off
	s_waitcnt vmcnt(8)
	s_waitcnt lgkmcnt(0)
	s_barrier
	s_setprio 1
	s_waitcnt lgkmcnt(0)
	v_mfma_f32_16x16x32_bf16 v[60:63], v[144:147], v[190:193], v[60:63]
	v_mfma_f32_16x16x32_bf16 v[52:55], v[162:165], v[190:193], v[52:55]
	v_mfma_f32_16x16x32_bf16 v[44:47], v[144:147], v[198:201], v[44:47]
	v_mfma_f32_16x16x32_bf16 v[36:39], v[162:165], v[198:201], v[36:39]
	v_mfma_f32_16x16x32_bf16 v[28:31], v[144:147], v[206:209], v[28:31]
	v_mfma_f32_16x16x32_bf16 v[20:23], v[162:165], v[206:209], v[20:23]
	v_mfma_f32_16x16x32_bf16 v[12:15], v[144:147], v[214:217], v[12:15]
	v_mfma_f32_16x16x32_bf16 v[4:7], v[162:165], v[214:217], v[4:7]
	v_mfma_f32_16x16x32_bf16 v[60:63], v[158:161], v[194:197], v[60:63]
	v_mfma_f32_16x16x32_bf16 v[52:55], v[166:169], v[194:197], v[52:55]
	v_mfma_f32_16x16x32_bf16 v[44:47], v[158:161], v[202:205], v[44:47]
	v_mfma_f32_16x16x32_bf16 v[36:39], v[166:169], v[202:205], v[36:39]
	v_mfma_f32_16x16x32_bf16 v[28:31], v[158:161], v[210:213], v[28:31]
	v_mfma_f32_16x16x32_bf16 v[20:23], v[166:169], v[210:213], v[20:23]
	v_mfma_f32_16x16x32_bf16 v[12:15], v[158:161], v[224:227], v[12:15]
	v_mfma_f32_16x16x32_bf16 v[4:7], v[166:169], v[224:227], v[4:7]
	s_setprio 0
	s_setprio 1
	v_mfma_f32_16x16x32_bf16 v[56:59], v[170:173], v[190:193], v[56:59]
	v_mfma_f32_16x16x32_bf16 v[48:51], v[178:181], v[190:193], v[48:51]
	v_mfma_f32_16x16x32_bf16 v[40:43], v[170:173], v[198:201], v[40:43]
	v_mfma_f32_16x16x32_bf16 v[32:35], v[178:181], v[198:201], v[32:35]
	v_mfma_f32_16x16x32_bf16 v[24:27], v[170:173], v[206:209], v[24:27]
	v_mfma_f32_16x16x32_bf16 v[16:19], v[178:181], v[206:209], v[16:19]
	v_mfma_f32_16x16x32_bf16 v[8:11], v[170:173], v[214:217], v[8:11]
	v_mfma_f32_16x16x32_bf16 v[0:3], v[178:181], v[214:217], v[0:3]
	v_mfma_f32_16x16x32_bf16 v[56:59], v[174:177], v[194:197], v[56:59]
	v_mfma_f32_16x16x32_bf16 v[48:51], v[186:189], v[194:197], v[48:51]
	v_mfma_f32_16x16x32_bf16 v[40:43], v[174:177], v[202:205], v[40:43]
	v_mfma_f32_16x16x32_bf16 v[32:35], v[186:189], v[202:205], v[32:35]
	v_mfma_f32_16x16x32_bf16 v[24:27], v[174:177], v[210:213], v[24:27]
	v_mfma_f32_16x16x32_bf16 v[16:19], v[186:189], v[210:213], v[16:19]
	v_mfma_f32_16x16x32_bf16 v[8:11], v[174:177], v[224:227], v[8:11]
	v_mfma_f32_16x16x32_bf16 v[0:3], v[186:189], v[224:227], v[0:3]
	s_setprio 0
	s_barrier
	s_add_i32 s64, 0, 0x18000
	v_add_u32_e32 v157, s64, v151
	s_add_i32 s65, 0, 0x1c000
	ds_read_b128 v[144:147], v157
	ds_read_b128 v[158:161], v157 offset:1024
	ds_read_b128 v[162:165], v157 offset:2048
	ds_read_b128 v[166:169], v157 offset:3072
	v_add_u32_e32 v157, s65, v151
	ds_read_b128 v[170:173], v157
	ds_read_b128 v[174:177], v157 offset:1024
	ds_read_b128 v[178:181], v157 offset:2048
	ds_read_b128 v[186:189], v157 offset:3072
	s_add_u32 s42, s42, s16
	s_addc_u32 s43, s43, s17
	s_mov_b32 m0, s44
	v_lshl_add_u64 v[236:237], s[42:43], 0, v[134:135]
	ds_read_b128 v[190:193], v155 offset:32768
	ds_read_b128 v[194:197], v155 offset:33792
	ds_read_b128 v[198:201], v155 offset:34816
	ds_read_b128 v[202:205], v155 offset:35840
	ds_read_b128 v[206:209], v155 offset:36864
	ds_read_b128 v[210:213], v155 offset:37888
	ds_read_b128 v[214:217], v155 offset:38912
	ds_read_b128 v[224:227], v155 offset:39936
	global_load_lds_dwordx4 v[236:237], off
	v_lshl_add_u64 v[236:237], s[42:43], 0, v[130:131]
	s_mov_b32 m0, s45
	s_nop 0
	global_load_lds_dwordx4 v[236:237], off
	s_waitcnt vmcnt(8)
	s_waitcnt lgkmcnt(0)
	s_barrier
	s_setprio 1
	s_waitcnt lgkmcnt(0)
	v_mfma_f32_16x16x32_bf16 v[120:123], v[144:147], v[190:193], v[120:123]
	v_mfma_f32_16x16x32_bf16 v[116:119], v[162:165], v[190:193], v[116:119]
	v_mfma_f32_16x16x32_bf16 v[108:111], v[144:147], v[198:201], v[108:111]
	v_mfma_f32_16x16x32_bf16 v[100:103], v[162:165], v[198:201], v[100:103]
	v_mfma_f32_16x16x32_bf16 v[92:95], v[144:147], v[206:209], v[92:95]
	v_mfma_f32_16x16x32_bf16 v[84:87], v[162:165], v[206:209], v[84:87]
	v_mfma_f32_16x16x32_bf16 v[76:79], v[144:147], v[214:217], v[76:79]
	v_mfma_f32_16x16x32_bf16 v[68:71], v[162:165], v[214:217], v[68:71]
	v_mfma_f32_16x16x32_bf16 v[120:123], v[158:161], v[194:197], v[120:123]
	v_mfma_f32_16x16x32_bf16 v[116:119], v[166:169], v[194:197], v[116:119]
	v_mfma_f32_16x16x32_bf16 v[108:111], v[158:161], v[202:205], v[108:111]
	v_mfma_f32_16x16x32_bf16 v[100:103], v[166:169], v[202:205], v[100:103]
	v_mfma_f32_16x16x32_bf16 v[92:95], v[158:161], v[210:213], v[92:95]
	v_mfma_f32_16x16x32_bf16 v[84:87], v[166:169], v[210:213], v[84:87]
	v_mfma_f32_16x16x32_bf16 v[76:79], v[158:161], v[224:227], v[76:79]
	v_mfma_f32_16x16x32_bf16 v[68:71], v[166:169], v[224:227], v[68:71]
	s_setprio 0
	s_setprio 1
	v_mfma_f32_16x16x32_bf16 v[124:127], v[170:173], v[190:193], v[124:127]
	v_mfma_f32_16x16x32_bf16 v[112:115], v[178:181], v[190:193], v[112:115]
	v_mfma_f32_16x16x32_bf16 v[104:107], v[170:173], v[198:201], v[104:107]
	v_mfma_f32_16x16x32_bf16 v[96:99], v[178:181], v[198:201], v[96:99]
	v_mfma_f32_16x16x32_bf16 v[88:91], v[170:173], v[206:209], v[88:91]
	v_mfma_f32_16x16x32_bf16 v[80:83], v[178:181], v[206:209], v[80:83]
	v_mfma_f32_16x16x32_bf16 v[72:75], v[170:173], v[214:217], v[72:75]
	v_mfma_f32_16x16x32_bf16 v[64:67], v[178:181], v[214:217], v[64:67]
	v_mfma_f32_16x16x32_bf16 v[124:127], v[174:177], v[194:197], v[124:127]
	v_mfma_f32_16x16x32_bf16 v[112:115], v[186:189], v[194:197], v[112:115]
	v_mfma_f32_16x16x32_bf16 v[104:107], v[174:177], v[202:205], v[104:107]
	v_mfma_f32_16x16x32_bf16 v[96:99], v[186:189], v[202:205], v[96:99]
	v_mfma_f32_16x16x32_bf16 v[88:91], v[174:177], v[210:213], v[88:91]
	v_mfma_f32_16x16x32_bf16 v[80:83], v[186:189], v[210:213], v[80:83]
	v_mfma_f32_16x16x32_bf16 v[72:75], v[174:177], v[224:227], v[72:75]
	v_mfma_f32_16x16x32_bf16 v[64:67], v[186:189], v[224:227], v[64:67]
	s_setprio 0
	s_barrier
	s_add_i32 s42, s64, s31
	v_lshl_add_u64 v[148:149], v[148:149], 0, s[36:37]
	s_mov_b32 m0, s42
	ds_read_b128 v[190:193], v155 offset:49152
	ds_read_b128 v[194:197], v155 offset:50176
	ds_read_b128 v[198:201], v155 offset:51200
	ds_read_b128 v[202:205], v155 offset:52224
	ds_read_b128 v[206:209], v155 offset:53248
	ds_read_b128 v[210:213], v155 offset:54272
	ds_read_b128 v[214:217], v155 offset:55296
	ds_read_b128 v[224:227], v155 offset:56320
	global_load_lds_dwordx4 v[148:149], off
	v_lshl_add_u64 v[148:149], v[182:183], 0, s[36:37]
	s_add_i32 m0, s42, 0x2000
	s_add_i32 s42, s65, s31
	global_load_lds_dwordx4 v[148:149], off
	v_lshl_add_u64 v[148:149], v[228:229], 0, s[36:37]
	s_mov_b32 m0, s42
	s_nop 0
	global_load_lds_dwordx4 v[148:149], off
	v_lshl_add_u64 v[148:149], v[230:231], 0, s[36:37]
	s_add_i32 m0, s42, 0x2000
	s_nop 0
	global_load_lds_dwordx4 v[148:149], off
	v_lshl_add_u64 v[148:149], v[232:233], 0, s[36:37]
	s_mov_b32 m0, s47
	s_nop 0
	global_load_lds_dwordx4 v[148:149], off
	v_lshl_add_u64 v[148:149], v[234:235], 0, s[36:37]
	s_mov_b32 m0, s48
	s_nop 0
	global_load_lds_dwordx4 v[148:149], off
	s_waitcnt vmcnt(8)
	s_waitcnt lgkmcnt(0)
	s_barrier
	s_setprio 1
	s_waitcnt lgkmcnt(0)
	v_mfma_f32_16x16x32_bf16 v[60:63], v[144:147], v[190:193], v[60:63]
	v_mfma_f32_16x16x32_bf16 v[52:55], v[162:165], v[190:193], v[52:55]
	v_mfma_f32_16x16x32_bf16 v[44:47], v[144:147], v[198:201], v[44:47]
	v_mfma_f32_16x16x32_bf16 v[36:39], v[162:165], v[198:201], v[36:39]
	v_mfma_f32_16x16x32_bf16 v[28:31], v[144:147], v[206:209], v[28:31]
	v_mfma_f32_16x16x32_bf16 v[20:23], v[162:165], v[206:209], v[20:23]
	v_mfma_f32_16x16x32_bf16 v[12:15], v[144:147], v[214:217], v[12:15]
	v_mfma_f32_16x16x32_bf16 v[4:7], v[162:165], v[214:217], v[4:7]
	v_mfma_f32_16x16x32_bf16 v[60:63], v[158:161], v[194:197], v[60:63]
	v_mfma_f32_16x16x32_bf16 v[52:55], v[166:169], v[194:197], v[52:55]
	v_mfma_f32_16x16x32_bf16 v[44:47], v[158:161], v[202:205], v[44:47]
	v_mfma_f32_16x16x32_bf16 v[36:39], v[166:169], v[202:205], v[36:39]
	v_mfma_f32_16x16x32_bf16 v[28:31], v[158:161], v[210:213], v[28:31]
	v_mfma_f32_16x16x32_bf16 v[20:23], v[166:169], v[210:213], v[20:23]
	v_mfma_f32_16x16x32_bf16 v[12:15], v[158:161], v[224:227], v[12:15]
	v_mfma_f32_16x16x32_bf16 v[4:7], v[166:169], v[224:227], v[4:7]
	s_setprio 0
	s_setprio 1
	v_mfma_f32_16x16x32_bf16 v[56:59], v[170:173], v[190:193], v[56:59]
	v_mfma_f32_16x16x32_bf16 v[48:51], v[178:181], v[190:193], v[48:51]
	v_mfma_f32_16x16x32_bf16 v[40:43], v[170:173], v[198:201], v[40:43]
	v_mfma_f32_16x16x32_bf16 v[32:35], v[178:181], v[198:201], v[32:35]
	v_mfma_f32_16x16x32_bf16 v[24:27], v[170:173], v[206:209], v[24:27]
	v_mfma_f32_16x16x32_bf16 v[16:19], v[178:181], v[206:209], v[16:19]
	v_mfma_f32_16x16x32_bf16 v[8:11], v[170:173], v[214:217], v[8:11]
	v_mfma_f32_16x16x32_bf16 v[0:3], v[178:181], v[214:217], v[0:3]
	v_mfma_f32_16x16x32_bf16 v[56:59], v[174:177], v[194:197], v[56:59]
	v_mfma_f32_16x16x32_bf16 v[48:51], v[186:189], v[194:197], v[48:51]
	v_mfma_f32_16x16x32_bf16 v[40:43], v[174:177], v[202:205], v[40:43]
	v_mfma_f32_16x16x32_bf16 v[32:35], v[186:189], v[202:205], v[32:35]
	v_mfma_f32_16x16x32_bf16 v[24:27], v[174:177], v[210:213], v[24:27]
	v_mfma_f32_16x16x32_bf16 v[16:19], v[186:189], v[210:213], v[16:19]
	v_mfma_f32_16x16x32_bf16 v[8:11], v[174:177], v[224:227], v[8:11]
	v_mfma_f32_16x16x32_bf16 v[0:3], v[186:189], v[224:227], v[0:3]
	s_add_u32 s40, s40, 0x100
	s_addc_u32 s41, s41, 0
	s_add_u32 s61, s61, 0x100
	s_addc_u32 s62, s62, 0
	s_cmp_ge_i32 s63, s49
	s_mov_b32 s42, s63
	s_setprio 0
	s_barrier
	s_cbranch_scc0 .LBB0_921

.LBB0_1003:
	ds_read_b128 v[144:147], v151
	ds_read_b128 v[154:157], v151 offset:1024
	ds_read_b128 v[158:161], v151 offset:2048
	ds_read_b128 v[162:165], v151 offset:3072
	ds_read_b128 v[166:169], v152
	ds_read_b128 v[170:173], v152 offset:1024
	ds_read_b128 v[174:177], v152 offset:2048
	ds_read_b128 v[178:181], v152 offset:3072
	s_add_i32 s61, s46, 2
	s_add_u32 s62, s44, 0x80
	s_addc_u32 s47, s45, 0
	s_cmp_eq_u32 s52, s46
	s_cselect_b32 s46, s8, s62
	s_cselect_b32 s47, s9, s47
	s_cselect_b32 s63, s43, s60
	s_cselect_b32 s62, s42, s59
	v_lshl_add_u64 v[182:183], s[44:45], 0, v[136:137]
	s_add_i32 m0, s3, 0xc000
	ds_read_b128 v[186:189], v153
	ds_read_b128 v[190:193], v153 offset:1024
	ds_read_b128 v[194:197], v153 offset:2048
	ds_read_b128 v[198:201], v153 offset:3072
	ds_read_b128 v[202:205], v153 offset:4096
	ds_read_b128 v[206:209], v153 offset:5120
	ds_read_b128 v[210:213], v153 offset:6144
	ds_read_b128 v[214:217], v153 offset:7168
	global_load_lds_dwordx4 v[182:183], off
	v_lshl_add_u64 v[182:183], s[44:45], 0, v[138:139]
	s_add_i32 m0, s3, 0xe000
	s_nop 0
	global_load_lds_dwordx4 v[182:183], off
	s_waitcnt vmcnt(8)
	s_waitcnt lgkmcnt(0)
	s_barrier
	s_setprio 1
	s_waitcnt lgkmcnt(0)
	v_mfma_f32_16x16x32_bf16 v[124:127], v[144:147], v[186:189], v[124:127]
	v_mfma_f32_16x16x32_bf16 v[120:123], v[158:161], v[186:189], v[120:123]
	v_mfma_f32_16x16x32_bf16 v[108:111], v[144:147], v[194:197], v[108:111]
	v_mfma_f32_16x16x32_bf16 v[104:107], v[158:161], v[194:197], v[104:107]
	v_mfma_f32_16x16x32_bf16 v[92:95], v[144:147], v[202:205], v[92:95]
	v_mfma_f32_16x16x32_bf16 v[88:91], v[158:161], v[202:205], v[88:91]
	v_mfma_f32_16x16x32_bf16 v[76:79], v[144:147], v[210:213], v[76:79]
	v_mfma_f32_16x16x32_bf16 v[72:75], v[158:161], v[210:213], v[72:75]
	v_mfma_f32_16x16x32_bf16 v[124:127], v[154:157], v[190:193], v[124:127]
	v_mfma_f32_16x16x32_bf16 v[120:123], v[162:165], v[190:193], v[120:123]
	v_mfma_f32_16x16x32_bf16 v[108:111], v[154:157], v[198:201], v[108:111]
	v_mfma_f32_16x16x32_bf16 v[104:107], v[162:165], v[198:201], v[104:107]
	v_mfma_f32_16x16x32_bf16 v[92:95], v[154:157], v[206:209], v[92:95]
	v_mfma_f32_16x16x32_bf16 v[88:91], v[162:165], v[206:209], v[88:91]
	v_mfma_f32_16x16x32_bf16 v[76:79], v[154:157], v[214:217], v[76:79]
	v_mfma_f32_16x16x32_bf16 v[72:75], v[162:165], v[214:217], v[72:75]
	s_setprio 0
	s_setprio 1
	v_mfma_f32_16x16x32_bf16 v[116:119], v[166:169], v[186:189], v[116:119]
	v_mfma_f32_16x16x32_bf16 v[112:115], v[174:177], v[186:189], v[112:115]
	v_mfma_f32_16x16x32_bf16 v[100:103], v[166:169], v[194:197], v[100:103]
	v_mfma_f32_16x16x32_bf16 v[96:99], v[174:177], v[194:197], v[96:99]
	v_mfma_f32_16x16x32_bf16 v[84:87], v[166:169], v[202:205], v[84:87]
	v_mfma_f32_16x16x32_bf16 v[80:83], v[174:177], v[202:205], v[80:83]
	v_mfma_f32_16x16x32_bf16 v[68:71], v[166:169], v[210:213], v[68:71]
	v_mfma_f32_16x16x32_bf16 v[64:67], v[174:177], v[210:213], v[64:67]
	v_mfma_f32_16x16x32_bf16 v[116:119], v[170:173], v[190:193], v[116:119]
	v_mfma_f32_16x16x32_bf16 v[112:115], v[178:181], v[190:193], v[112:115]
	v_mfma_f32_16x16x32_bf16 v[100:103], v[170:173], v[198:201], v[100:103]
	v_mfma_f32_16x16x32_bf16 v[96:99], v[178:181], v[198:201], v[96:99]
	v_mfma_f32_16x16x32_bf16 v[84:87], v[170:173], v[206:209], v[84:87]
	v_mfma_f32_16x16x32_bf16 v[80:83], v[178:181], v[206:209], v[80:83]
	v_mfma_f32_16x16x32_bf16 v[68:71], v[170:173], v[214:217], v[68:71]
	v_mfma_f32_16x16x32_bf16 v[64:67], v[178:181], v[214:217], v[64:67]
	s_setprio 0
	s_barrier
	s_add_i32 s64, s53, s31
	v_lshl_add_u64 v[182:183], s[62:63], 0, v[130:131]
	s_mov_b32 m0, s64
	ds_read_b128 v[186:189], v153 offset:16384
	ds_read_b128 v[190:193], v153 offset:17408
	ds_read_b128 v[194:197], v153 offset:18432
	ds_read_b128 v[198:201], v153 offset:19456
	ds_read_b128 v[202:205], v153 offset:20480
	ds_read_b128 v[206:209], v153 offset:21504
	ds_read_b128 v[210:213], v153 offset:22528
	ds_read_b128 v[214:217], v153 offset:23552
	global_load_lds_dwordx4 v[182:183], off
	s_add_i32 m0, s64, 0x2000
	v_lshl_add_u64 v[224:225], s[62:63], 0, v[134:135]
	s_add_u32 s62, s62, s16
	s_addc_u32 s63, s63, s17
	s_add_i32 s64, s54, s31
	global_load_lds_dwordx4 v[224:225], off
	v_lshl_add_u64 v[226:227], s[62:63], 0, v[130:131]
	s_mov_b32 m0, s64
	v_lshl_add_u64 v[228:229], s[62:63], 0, v[134:135]
	global_load_lds_dwordx4 v[226:227], off
	s_add_i32 m0, s64, 0x2000
	v_lshl_add_u64 v[230:231], s[46:47], 0, v[128:129]
	global_load_lds_dwordx4 v[228:229], off
	s_mov_b32 m0, s3
	v_lshl_add_u64 v[232:233], s[46:47], 0, v[132:133]
	global_load_lds_dwordx4 v[230:231], off
	s_mov_b32 m0, s28
	s_nop 0
	global_load_lds_dwordx4 v[232:233], off
	s_waitcnt vmcnt(8)
	s_waitcnt lgkmcnt(0)
	s_barrier
	s_setprio 1
	s_waitcnt lgkmcnt(0)
	v_mfma_f32_16x16x32_bf16 v[60:63], v[144:147], v[186:189], v[60:63]
	v_mfma_f32_16x16x32_bf16 v[56:59], v[158:161], v[186:189], v[56:59]
	v_mfma_f32_16x16x32_bf16 v[44:47], v[144:147], v[194:197], v[44:47]
	v_mfma_f32_16x16x32_bf16 v[40:43], v[158:161], v[194:197], v[40:43]
	v_mfma_f32_16x16x32_bf16 v[28:31], v[144:147], v[202:205], v[28:31]
	v_mfma_f32_16x16x32_bf16 v[24:27], v[158:161], v[202:205], v[24:27]
	v_mfma_f32_16x16x32_bf16 v[12:15], v[144:147], v[210:213], v[12:15]
	v_mfma_f32_16x16x32_bf16 v[8:11], v[158:161], v[210:213], v[8:11]
	v_mfma_f32_16x16x32_bf16 v[60:63], v[154:157], v[190:193], v[60:63]
	v_mfma_f32_16x16x32_bf16 v[56:59], v[162:165], v[190:193], v[56:59]
	v_mfma_f32_16x16x32_bf16 v[44:47], v[154:157], v[198:201], v[44:47]
	v_mfma_f32_16x16x32_bf16 v[40:43], v[162:165], v[198:201], v[40:43]
	v_mfma_f32_16x16x32_bf16 v[28:31], v[154:157], v[206:209], v[28:31]
	v_mfma_f32_16x16x32_bf16 v[24:27], v[162:165], v[206:209], v[24:27]
	v_mfma_f32_16x16x32_bf16 v[12:15], v[154:157], v[214:217], v[12:15]
	v_mfma_f32_16x16x32_bf16 v[8:11], v[162:165], v[214:217], v[8:11]
	s_setprio 0
	s_setprio 1
	v_mfma_f32_16x16x32_bf16 v[52:55], v[166:169], v[186:189], v[52:55]
	v_mfma_f32_16x16x32_bf16 v[48:51], v[174:177], v[186:189], v[48:51]
	v_mfma_f32_16x16x32_bf16 v[36:39], v[166:169], v[194:197], v[36:39]
	v_mfma_f32_16x16x32_bf16 v[32:35], v[174:177], v[194:197], v[32:35]
	v_mfma_f32_16x16x32_bf16 v[20:23], v[166:169], v[202:205], v[20:23]
	v_mfma_f32_16x16x32_bf16 v[16:19], v[174:177], v[202:205], v[16:19]
	v_mfma_f32_16x16x32_bf16 v[4:7], v[166:169], v[210:213], v[4:7]
	v_mfma_f32_16x16x32_bf16 v[0:3], v[174:177], v[210:213], v[0:3]
	v_mfma_f32_16x16x32_bf16 v[52:55], v[170:173], v[190:193], v[52:55]
	v_mfma_f32_16x16x32_bf16 v[48:51], v[178:181], v[190:193], v[48:51]
	v_mfma_f32_16x16x32_bf16 v[36:39], v[170:173], v[198:201], v[36:39]
	v_mfma_f32_16x16x32_bf16 v[32:35], v[178:181], v[198:201], v[32:35]
	v_mfma_f32_16x16x32_bf16 v[20:23], v[170:173], v[206:209], v[20:23]
	v_mfma_f32_16x16x32_bf16 v[16:19], v[178:181], v[206:209], v[16:19]
	v_mfma_f32_16x16x32_bf16 v[4:7], v[170:173], v[214:217], v[4:7]
	v_mfma_f32_16x16x32_bf16 v[0:3], v[178:181], v[214:217], v[0:3]
	s_setprio 0
	s_barrier
	s_add_i32 s62, 0, 0x18000
	s_add_i32 s63, 0, 0x1c000
	v_add_u32_e32 v162, s62, v149
	v_add_u32_e32 v178, s63, v149
	ds_read_b128 v[144:147], v162
	ds_read_b128 v[154:157], v162 offset:1024
	ds_read_b128 v[158:161], v162 offset:2048
	ds_read_b128 v[162:165], v162 offset:3072
	ds_read_b128 v[166:169], v178
	ds_read_b128 v[170:173], v178 offset:1024
	ds_read_b128 v[174:177], v178 offset:2048
	ds_read_b128 v[178:181], v178 offset:3072
	s_add_u32 s46, s46, s16
	s_addc_u32 s47, s47, s17
	s_mov_b32 m0, s33
	v_lshl_add_u64 v[234:235], s[46:47], 0, v[128:129]
	ds_read_b128 v[186:189], v153 offset:32768
	ds_read_b128 v[190:193], v153 offset:33792
	ds_read_b128 v[194:197], v153 offset:34816
	ds_read_b128 v[198:201], v153 offset:35840
	ds_read_b128 v[202:205], v153 offset:36864
	ds_read_b128 v[206:209], v153 offset:37888
	ds_read_b128 v[210:213], v153 offset:38912
	ds_read_b128 v[214:217], v153 offset:39936
	global_load_lds_dwordx4 v[234:235], off
	v_lshl_add_u64 v[234:235], s[46:47], 0, v[132:133]
	s_mov_b32 m0, s48
	s_nop 0
	global_load_lds_dwordx4 v[234:235], off
	s_waitcnt vmcnt(8)
	s_waitcnt lgkmcnt(0)
	s_barrier
	s_setprio 1
	s_waitcnt lgkmcnt(0)
	v_mfma_f32_16x16x32_bf16 v[124:127], v[144:147], v[186:189], v[124:127]
	v_mfma_f32_16x16x32_bf16 v[120:123], v[158:161], v[186:189], v[120:123]
	v_mfma_f32_16x16x32_bf16 v[108:111], v[144:147], v[194:197], v[108:111]
	v_mfma_f32_16x16x32_bf16 v[104:107], v[158:161], v[194:197], v[104:107]
	v_mfma_f32_16x16x32_bf16 v[92:95], v[144:147], v[202:205], v[92:95]
	v_mfma_f32_16x16x32_bf16 v[88:91], v[158:161], v[202:205], v[88:91]
	v_mfma_f32_16x16x32_bf16 v[76:79], v[144:147], v[210:213], v[76:79]
	v_mfma_f32_16x16x32_bf16 v[72:75], v[158:161], v[210:213], v[72:75]
	v_mfma_f32_16x16x32_bf16 v[124:127], v[154:157], v[190:193], v[124:127]
	v_mfma_f32_16x16x32_bf16 v[120:123], v[162:165], v[190:193], v[120:123]
	v_mfma_f32_16x16x32_bf16 v[108:111], v[154:157], v[198:201], v[108:111]
	v_mfma_f32_16x16x32_bf16 v[104:107], v[162:165], v[198:201], v[104:107]
	v_mfma_f32_16x16x32_bf16 v[92:95], v[154:157], v[206:209], v[92:95]
	v_mfma_f32_16x16x32_bf16 v[88:91], v[162:165], v[206:209], v[88:91]
	v_mfma_f32_16x16x32_bf16 v[76:79], v[154:157], v[214:217], v[76:79]
	v_mfma_f32_16x16x32_bf16 v[72:75], v[162:165], v[214:217], v[72:75]
	s_setprio 0
	s_setprio 1
	v_mfma_f32_16x16x32_bf16 v[116:119], v[166:169], v[186:189], v[116:119]
	v_mfma_f32_16x16x32_bf16 v[112:115], v[174:177], v[186:189], v[112:115]
	v_mfma_f32_16x16x32_bf16 v[100:103], v[166:169], v[194:197], v[100:103]
	v_mfma_f32_16x16x32_bf16 v[96:99], v[174:177], v[194:197], v[96:99]
	v_mfma_f32_16x16x32_bf16 v[84:87], v[166:169], v[202:205], v[84:87]
	v_mfma_f32_16x16x32_bf16 v[80:83], v[174:177], v[202:205], v[80:83]
	v_mfma_f32_16x16x32_bf16 v[68:71], v[166:169], v[210:213], v[68:71]
	v_mfma_f32_16x16x32_bf16 v[64:67], v[174:177], v[210:213], v[64:67]
	v_mfma_f32_16x16x32_bf16 v[116:119], v[170:173], v[190:193], v[116:119]
	v_mfma_f32_16x16x32_bf16 v[112:115], v[178:181], v[190:193], v[112:115]
	v_mfma_f32_16x16x32_bf16 v[100:103], v[170:173], v[198:201], v[100:103]
	v_mfma_f32_16x16x32_bf16 v[96:99], v[178:181], v[198:201], v[96:99]
	v_mfma_f32_16x16x32_bf16 v[84:87], v[170:173], v[206:209], v[84:87]
	v_mfma_f32_16x16x32_bf16 v[80:83], v[178:181], v[206:209], v[80:83]
	v_mfma_f32_16x16x32_bf16 v[68:71], v[170:173], v[214:217], v[68:71]
	v_mfma_f32_16x16x32_bf16 v[64:67], v[178:181], v[214:217], v[64:67]
	s_setprio 0
	s_barrier
	s_add_i32 s46, s62, s31
	v_lshl_add_u64 v[182:183], v[182:183], 0, s[40:41]
	s_mov_b32 m0, s46
	ds_read_b128 v[186:189], v153 offset:49152
	ds_read_b128 v[190:193], v153 offset:50176
	ds_read_b128 v[194:197], v153 offset:51200
	ds_read_b128 v[198:201], v153 offset:52224
	ds_read_b128 v[202:205], v153 offset:53248
	ds_read_b128 v[206:209], v153 offset:54272
	ds_read_b128 v[210:213], v153 offset:55296
	ds_read_b128 v[214:217], v153 offset:56320
	global_load_lds_dwordx4 v[182:183], off
	v_lshl_add_u64 v[182:183], v[224:225], 0, s[40:41]
	s_add_i32 m0, s46, 0x2000
	s_add_i32 s46, s63, s31
	global_load_lds_dwordx4 v[182:183], off
	v_lshl_add_u64 v[182:183], v[226:227], 0, s[40:41]
	s_mov_b32 m0, s46
	s_nop 0
	global_load_lds_dwordx4 v[182:183], off
	v_lshl_add_u64 v[182:183], v[228:229], 0, s[40:41]
	s_add_i32 m0, s46, 0x2000
	s_nop 0
	global_load_lds_dwordx4 v[182:183], off
	v_lshl_add_u64 v[182:183], v[230:231], 0, s[40:41]
	s_mov_b32 m0, s49
	s_nop 0
	global_load_lds_dwordx4 v[182:183], off
	v_lshl_add_u64 v[182:183], v[232:233], 0, s[40:41]
	s_mov_b32 m0, s50
	s_nop 0
	global_load_lds_dwordx4 v[182:183], off
	s_waitcnt vmcnt(8)
	s_waitcnt lgkmcnt(0)
	s_barrier
	s_setprio 1
	s_waitcnt lgkmcnt(0)
	v_mfma_f32_16x16x32_bf16 v[60:63], v[144:147], v[186:189], v[60:63]
	v_mfma_f32_16x16x32_bf16 v[56:59], v[158:161], v[186:189], v[56:59]
	v_mfma_f32_16x16x32_bf16 v[44:47], v[144:147], v[194:197], v[44:47]
	v_mfma_f32_16x16x32_bf16 v[40:43], v[158:161], v[194:197], v[40:43]
	v_mfma_f32_16x16x32_bf16 v[28:31], v[144:147], v[202:205], v[28:31]
	v_mfma_f32_16x16x32_bf16 v[24:27], v[158:161], v[202:205], v[24:27]
	v_mfma_f32_16x16x32_bf16 v[12:15], v[144:147], v[210:213], v[12:15]
	v_mfma_f32_16x16x32_bf16 v[8:11], v[158:161], v[210:213], v[8:11]
	v_mfma_f32_16x16x32_bf16 v[60:63], v[154:157], v[190:193], v[60:63]
	v_mfma_f32_16x16x32_bf16 v[56:59], v[162:165], v[190:193], v[56:59]
	v_mfma_f32_16x16x32_bf16 v[44:47], v[154:157], v[198:201], v[44:47]
	v_mfma_f32_16x16x32_bf16 v[40:43], v[162:165], v[198:201], v[40:43]
	v_mfma_f32_16x16x32_bf16 v[28:31], v[154:157], v[206:209], v[28:31]
	v_mfma_f32_16x16x32_bf16 v[24:27], v[162:165], v[206:209], v[24:27]
	v_mfma_f32_16x16x32_bf16 v[12:15], v[154:157], v[214:217], v[12:15]
	v_mfma_f32_16x16x32_bf16 v[8:11], v[162:165], v[214:217], v[8:11]
	s_setprio 0
	s_setprio 1
	v_mfma_f32_16x16x32_bf16 v[52:55], v[166:169], v[186:189], v[52:55]
	v_mfma_f32_16x16x32_bf16 v[48:51], v[174:177], v[186:189], v[48:51]
	v_mfma_f32_16x16x32_bf16 v[36:39], v[166:169], v[194:197], v[36:39]
	v_mfma_f32_16x16x32_bf16 v[32:35], v[174:177], v[194:197], v[32:35]
	v_mfma_f32_16x16x32_bf16 v[20:23], v[166:169], v[202:205], v[20:23]
	v_mfma_f32_16x16x32_bf16 v[16:19], v[174:177], v[202:205], v[16:19]
	v_mfma_f32_16x16x32_bf16 v[4:7], v[166:169], v[210:213], v[4:7]
	v_mfma_f32_16x16x32_bf16 v[0:3], v[174:177], v[210:213], v[0:3]
	v_mfma_f32_16x16x32_bf16 v[52:55], v[170:173], v[190:193], v[52:55]
	v_mfma_f32_16x16x32_bf16 v[48:51], v[178:181], v[190:193], v[48:51]
	v_mfma_f32_16x16x32_bf16 v[36:39], v[170:173], v[198:201], v[36:39]
	v_mfma_f32_16x16x32_bf16 v[32:35], v[178:181], v[198:201], v[32:35]
	v_mfma_f32_16x16x32_bf16 v[20:23], v[170:173], v[206:209], v[20:23]
	v_mfma_f32_16x16x32_bf16 v[16:19], v[178:181], v[206:209], v[16:19]
	v_mfma_f32_16x16x32_bf16 v[4:7], v[170:173], v[214:217], v[4:7]
	v_mfma_f32_16x16x32_bf16 v[0:3], v[178:181], v[214:217], v[0:3]
	s_add_u32 s44, s44, 0x100
	s_addc_u32 s45, s45, 0
	s_add_u32 s59, s59, 0x100
	s_addc_u32 s60, s60, 0
	s_cmp_ge_i32 s61, s51
	s_mov_b32 s46, s61
	s_setprio 0
	s_barrier
	s_cbranch_scc0 .LBB0_1003

.LBB0_1112:
	ds_read_b128 v[144:147], v151
	ds_read_b128 v[156:159], v151 offset:1024
	ds_read_b128 v[160:163], v151 offset:2048
	ds_read_b128 v[164:167], v151 offset:3072
	ds_read_b128 v[168:171], v152
	ds_read_b128 v[172:175], v152 offset:1024
	ds_read_b128 v[176:179], v152 offset:2048
	ds_read_b128 v[180:183], v152 offset:3072
	s_add_i32 s49, s46, 2
	s_add_u32 s52, s4, 0x80
	s_addc_u32 s47, s5, 0
	s_cmp_eq_u32 s60, s46
	s_cselect_b32 s46, s42, s52
	s_cselect_b32 s47, s43, s47
	s_cselect_b32 s53, s45, s48
	s_cselect_b32 s52, s44, s33
	v_lshl_add_u64 v[224:225], s[4:5], 0, v[136:137]
	s_add_i32 m0, s50, 0xc000
	ds_read_b128 v[186:189], v153
	ds_read_b128 v[190:193], v153 offset:1024
	ds_read_b128 v[194:197], v153 offset:2048
	ds_read_b128 v[198:201], v153 offset:3072
	ds_read_b128 v[202:205], v153 offset:4096
	ds_read_b128 v[206:209], v153 offset:5120
	ds_read_b128 v[210:213], v153 offset:6144
	ds_read_b128 v[214:217], v153 offset:7168
	global_load_lds_dwordx4 v[224:225], off
	v_lshl_add_u64 v[224:225], s[4:5], 0, v[138:139]
	s_add_i32 m0, s50, 0xe000
	s_nop 0
	global_load_lds_dwordx4 v[224:225], off
	s_waitcnt vmcnt(8)
	s_waitcnt lgkmcnt(0)
	s_barrier
	s_setprio 1
	s_waitcnt lgkmcnt(0)
	v_mfma_f32_16x16x32_bf16 v[124:127], v[144:147], v[186:189], v[124:127]
	v_mfma_f32_16x16x32_bf16 v[120:123], v[160:163], v[186:189], v[120:123]
	v_mfma_f32_16x16x32_bf16 v[108:111], v[144:147], v[194:197], v[108:111]
	v_mfma_f32_16x16x32_bf16 v[104:107], v[160:163], v[194:197], v[104:107]
	v_mfma_f32_16x16x32_bf16 v[92:95], v[144:147], v[202:205], v[92:95]
	v_mfma_f32_16x16x32_bf16 v[88:91], v[160:163], v[202:205], v[88:91]
	v_mfma_f32_16x16x32_bf16 v[76:79], v[144:147], v[210:213], v[76:79]
	v_mfma_f32_16x16x32_bf16 v[72:75], v[160:163], v[210:213], v[72:75]
	v_mfma_f32_16x16x32_bf16 v[124:127], v[156:159], v[190:193], v[124:127]
	v_mfma_f32_16x16x32_bf16 v[120:123], v[164:167], v[190:193], v[120:123]
	v_mfma_f32_16x16x32_bf16 v[108:111], v[156:159], v[198:201], v[108:111]
	v_mfma_f32_16x16x32_bf16 v[104:107], v[164:167], v[198:201], v[104:107]
	v_mfma_f32_16x16x32_bf16 v[92:95], v[156:159], v[206:209], v[92:95]
	v_mfma_f32_16x16x32_bf16 v[88:91], v[164:167], v[206:209], v[88:91]
	v_mfma_f32_16x16x32_bf16 v[76:79], v[156:159], v[214:217], v[76:79]
	v_mfma_f32_16x16x32_bf16 v[72:75], v[164:167], v[214:217], v[72:75]
	s_setprio 0
	s_setprio 1
	v_mfma_f32_16x16x32_bf16 v[116:119], v[168:171], v[186:189], v[116:119]
	v_mfma_f32_16x16x32_bf16 v[112:115], v[176:179], v[186:189], v[112:115]
	v_mfma_f32_16x16x32_bf16 v[100:103], v[168:171], v[194:197], v[100:103]
	v_mfma_f32_16x16x32_bf16 v[96:99], v[176:179], v[194:197], v[96:99]
	v_mfma_f32_16x16x32_bf16 v[84:87], v[168:171], v[202:205], v[84:87]
	v_mfma_f32_16x16x32_bf16 v[80:83], v[176:179], v[202:205], v[80:83]
	v_mfma_f32_16x16x32_bf16 v[68:71], v[168:171], v[210:213], v[68:71]
	v_mfma_f32_16x16x32_bf16 v[64:67], v[176:179], v[210:213], v[64:67]
	v_mfma_f32_16x16x32_bf16 v[116:119], v[172:175], v[190:193], v[116:119]
	v_mfma_f32_16x16x32_bf16 v[112:115], v[180:183], v[190:193], v[112:115]
	v_mfma_f32_16x16x32_bf16 v[100:103], v[172:175], v[198:201], v[100:103]
	v_mfma_f32_16x16x32_bf16 v[96:99], v[180:183], v[198:201], v[96:99]
	v_mfma_f32_16x16x32_bf16 v[84:87], v[172:175], v[206:209], v[84:87]
	v_mfma_f32_16x16x32_bf16 v[80:83], v[180:183], v[206:209], v[80:83]
	v_mfma_f32_16x16x32_bf16 v[68:71], v[172:175], v[214:217], v[68:71]
	v_mfma_f32_16x16x32_bf16 v[64:67], v[180:183], v[214:217], v[64:67]
	s_setprio 0
	s_barrier
	s_add_i32 s65, s61, s31
	v_lshl_add_u64 v[224:225], s[52:53], 0, v[130:131]
	s_mov_b32 m0, s65
	ds_read_b128 v[186:189], v153 offset:16384
	ds_read_b128 v[190:193], v153 offset:17408
	ds_read_b128 v[194:197], v153 offset:18432
	ds_read_b128 v[198:201], v153 offset:19456
	ds_read_b128 v[202:205], v153 offset:20480
	ds_read_b128 v[206:209], v153 offset:21504
	ds_read_b128 v[210:213], v153 offset:22528
	ds_read_b128 v[214:217], v153 offset:23552
	global_load_lds_dwordx4 v[224:225], off
	s_add_i32 m0, s65, 0x2000
	v_lshl_add_u64 v[226:227], s[52:53], 0, v[134:135]
	s_add_u32 s52, s52, s14
	s_addc_u32 s53, s53, s15
	s_add_i32 s65, s62, s31
	global_load_lds_dwordx4 v[226:227], off
	v_lshl_add_u64 v[228:229], s[52:53], 0, v[130:131]
	s_mov_b32 m0, s65
	v_lshl_add_u64 v[230:231], s[52:53], 0, v[134:135]
	global_load_lds_dwordx4 v[228:229], off
	s_add_i32 m0, s65, 0x2000
	v_lshl_add_u64 v[232:233], s[46:47], 0, v[128:129]
	global_load_lds_dwordx4 v[230:231], off
	s_mov_b32 m0, s50
	v_lshl_add_u64 v[234:235], s[46:47], 0, v[132:133]
	global_load_lds_dwordx4 v[232:233], off
	s_mov_b32 m0, s51
	s_nop 0
	global_load_lds_dwordx4 v[234:235], off
	s_waitcnt vmcnt(8)
	s_waitcnt lgkmcnt(0)
	s_barrier
	s_setprio 1
	s_waitcnt lgkmcnt(0)
	v_mfma_f32_16x16x32_bf16 v[60:63], v[144:147], v[186:189], v[60:63]
	v_mfma_f32_16x16x32_bf16 v[56:59], v[160:163], v[186:189], v[56:59]
	v_mfma_f32_16x16x32_bf16 v[44:47], v[144:147], v[194:197], v[44:47]
	v_mfma_f32_16x16x32_bf16 v[40:43], v[160:163], v[194:197], v[40:43]
	v_mfma_f32_16x16x32_bf16 v[28:31], v[144:147], v[202:205], v[28:31]
	v_mfma_f32_16x16x32_bf16 v[24:27], v[160:163], v[202:205], v[24:27]
	v_mfma_f32_16x16x32_bf16 v[12:15], v[144:147], v[210:213], v[12:15]
	v_mfma_f32_16x16x32_bf16 v[8:11], v[160:163], v[210:213], v[8:11]
	v_mfma_f32_16x16x32_bf16 v[60:63], v[156:159], v[190:193], v[60:63]
	v_mfma_f32_16x16x32_bf16 v[56:59], v[164:167], v[190:193], v[56:59]
	v_mfma_f32_16x16x32_bf16 v[44:47], v[156:159], v[198:201], v[44:47]
	v_mfma_f32_16x16x32_bf16 v[40:43], v[164:167], v[198:201], v[40:43]
	v_mfma_f32_16x16x32_bf16 v[28:31], v[156:159], v[206:209], v[28:31]
	v_mfma_f32_16x16x32_bf16 v[24:27], v[164:167], v[206:209], v[24:27]
	v_mfma_f32_16x16x32_bf16 v[12:15], v[156:159], v[214:217], v[12:15]
	v_mfma_f32_16x16x32_bf16 v[8:11], v[164:167], v[214:217], v[8:11]
	s_setprio 0
	s_setprio 1
	v_mfma_f32_16x16x32_bf16 v[52:55], v[168:171], v[186:189], v[52:55]
	v_mfma_f32_16x16x32_bf16 v[48:51], v[176:179], v[186:189], v[48:51]
	v_mfma_f32_16x16x32_bf16 v[36:39], v[168:171], v[194:197], v[36:39]
	v_mfma_f32_16x16x32_bf16 v[32:35], v[176:179], v[194:197], v[32:35]
	v_mfma_f32_16x16x32_bf16 v[20:23], v[168:171], v[202:205], v[20:23]
	v_mfma_f32_16x16x32_bf16 v[16:19], v[176:179], v[202:205], v[16:19]
	v_mfma_f32_16x16x32_bf16 v[4:7], v[168:171], v[210:213], v[4:7]
	v_mfma_f32_16x16x32_bf16 v[0:3], v[176:179], v[210:213], v[0:3]
	v_mfma_f32_16x16x32_bf16 v[52:55], v[172:175], v[190:193], v[52:55]
	v_mfma_f32_16x16x32_bf16 v[48:51], v[180:183], v[190:193], v[48:51]
	v_mfma_f32_16x16x32_bf16 v[36:39], v[172:175], v[198:201], v[36:39]
	v_mfma_f32_16x16x32_bf16 v[32:35], v[180:183], v[198:201], v[32:35]
	v_mfma_f32_16x16x32_bf16 v[20:23], v[172:175], v[206:209], v[20:23]
	v_mfma_f32_16x16x32_bf16 v[16:19], v[180:183], v[206:209], v[16:19]
	v_mfma_f32_16x16x32_bf16 v[4:7], v[172:175], v[214:217], v[4:7]
	v_mfma_f32_16x16x32_bf16 v[0:3], v[180:183], v[214:217], v[0:3]
	s_setprio 0
	s_barrier
	s_add_i32 s52, 0, 0x18000
	v_add_u32_e32 v155, s52, v149
	s_add_i32 s53, 0, 0x1c000
	ds_read_b128 v[144:147], v155
	ds_read_b128 v[156:159], v155 offset:1024
	ds_read_b128 v[160:163], v155 offset:2048
	ds_read_b128 v[164:167], v155 offset:3072
	v_add_u32_e32 v155, s53, v149
	ds_read_b128 v[168:171], v155
	ds_read_b128 v[172:175], v155 offset:1024
	ds_read_b128 v[176:179], v155 offset:2048
	ds_read_b128 v[180:183], v155 offset:3072
	s_add_u32 s46, s46, s14
	s_addc_u32 s47, s47, s15
	s_mov_b32 m0, s54
	v_lshl_add_u64 v[236:237], s[46:47], 0, v[128:129]
	ds_read_b128 v[186:189], v153 offset:32768
	ds_read_b128 v[190:193], v153 offset:33792
	ds_read_b128 v[194:197], v153 offset:34816
	ds_read_b128 v[198:201], v153 offset:35840
	ds_read_b128 v[202:205], v153 offset:36864
	ds_read_b128 v[206:209], v153 offset:37888
	ds_read_b128 v[210:213], v153 offset:38912
	ds_read_b128 v[214:217], v153 offset:39936
	global_load_lds_dwordx4 v[236:237], off
	v_lshl_add_u64 v[236:237], s[46:47], 0, v[132:133]
	s_mov_b32 m0, s55
	s_nop 0
	global_load_lds_dwordx4 v[236:237], off
	s_waitcnt vmcnt(8)
	s_waitcnt lgkmcnt(0)
	s_barrier
	s_setprio 1
	s_waitcnt lgkmcnt(0)
	v_mfma_f32_16x16x32_bf16 v[124:127], v[144:147], v[186:189], v[124:127]
	v_mfma_f32_16x16x32_bf16 v[120:123], v[160:163], v[186:189], v[120:123]
	v_mfma_f32_16x16x32_bf16 v[108:111], v[144:147], v[194:197], v[108:111]
	v_mfma_f32_16x16x32_bf16 v[104:107], v[160:163], v[194:197], v[104:107]
	v_mfma_f32_16x16x32_bf16 v[92:95], v[144:147], v[202:205], v[92:95]
	v_mfma_f32_16x16x32_bf16 v[88:91], v[160:163], v[202:205], v[88:91]
	v_mfma_f32_16x16x32_bf16 v[76:79], v[144:147], v[210:213], v[76:79]
	v_mfma_f32_16x16x32_bf16 v[72:75], v[160:163], v[210:213], v[72:75]
	v_mfma_f32_16x16x32_bf16 v[124:127], v[156:159], v[190:193], v[124:127]
	v_mfma_f32_16x16x32_bf16 v[120:123], v[164:167], v[190:193], v[120:123]
	v_mfma_f32_16x16x32_bf16 v[108:111], v[156:159], v[198:201], v[108:111]
	v_mfma_f32_16x16x32_bf16 v[104:107], v[164:167], v[198:201], v[104:107]
	v_mfma_f32_16x16x32_bf16 v[92:95], v[156:159], v[206:209], v[92:95]
	v_mfma_f32_16x16x32_bf16 v[88:91], v[164:167], v[206:209], v[88:91]
	v_mfma_f32_16x16x32_bf16 v[76:79], v[156:159], v[214:217], v[76:79]
	v_mfma_f32_16x16x32_bf16 v[72:75], v[164:167], v[214:217], v[72:75]
	s_setprio 0
	s_setprio 1
	v_mfma_f32_16x16x32_bf16 v[116:119], v[168:171], v[186:189], v[116:119]
	v_mfma_f32_16x16x32_bf16 v[112:115], v[176:179], v[186:189], v[112:115]
	v_mfma_f32_16x16x32_bf16 v[100:103], v[168:171], v[194:197], v[100:103]
	v_mfma_f32_16x16x32_bf16 v[96:99], v[176:179], v[194:197], v[96:99]
	v_mfma_f32_16x16x32_bf16 v[84:87], v[168:171], v[202:205], v[84:87]
	v_mfma_f32_16x16x32_bf16 v[80:83], v[176:179], v[202:205], v[80:83]
	v_mfma_f32_16x16x32_bf16 v[68:71], v[168:171], v[210:213], v[68:71]
	v_mfma_f32_16x16x32_bf16 v[64:67], v[176:179], v[210:213], v[64:67]
	v_mfma_f32_16x16x32_bf16 v[116:119], v[172:175], v[190:193], v[116:119]
	v_mfma_f32_16x16x32_bf16 v[112:115], v[180:183], v[190:193], v[112:115]
	v_mfma_f32_16x16x32_bf16 v[100:103], v[172:175], v[198:201], v[100:103]
	v_mfma_f32_16x16x32_bf16 v[96:99], v[180:183], v[198:201], v[96:99]
	v_mfma_f32_16x16x32_bf16 v[84:87], v[172:175], v[206:209], v[84:87]
	v_mfma_f32_16x16x32_bf16 v[80:83], v[180:183], v[206:209], v[80:83]
	v_mfma_f32_16x16x32_bf16 v[68:71], v[172:175], v[214:217], v[68:71]
	v_mfma_f32_16x16x32_bf16 v[64:67], v[180:183], v[214:217], v[64:67]
	s_setprio 0
	s_barrier
	s_add_i32 s46, s52, s31
	v_lshl_add_u64 v[224:225], v[224:225], 0, s[36:37]
	s_mov_b32 m0, s46
	ds_read_b128 v[186:189], v153 offset:49152
	ds_read_b128 v[190:193], v153 offset:50176
	ds_read_b128 v[194:197], v153 offset:51200
	ds_read_b128 v[198:201], v153 offset:52224
	ds_read_b128 v[202:205], v153 offset:53248
	ds_read_b128 v[206:209], v153 offset:54272
	ds_read_b128 v[210:213], v153 offset:55296
	ds_read_b128 v[214:217], v153 offset:56320
	global_load_lds_dwordx4 v[224:225], off
	v_lshl_add_u64 v[224:225], v[226:227], 0, s[36:37]
	s_add_i32 m0, s46, 0x2000
	s_add_i32 s46, s53, s31
	global_load_lds_dwordx4 v[224:225], off
	v_lshl_add_u64 v[224:225], v[228:229], 0, s[36:37]
	s_mov_b32 m0, s46
	s_nop 0
	global_load_lds_dwordx4 v[224:225], off
	v_lshl_add_u64 v[224:225], v[230:231], 0, s[36:37]
	s_add_i32 m0, s46, 0x2000
	s_nop 0
	global_load_lds_dwordx4 v[224:225], off
	v_lshl_add_u64 v[224:225], v[232:233], 0, s[36:37]
	s_mov_b32 m0, s57
	s_nop 0
	global_load_lds_dwordx4 v[224:225], off
	v_lshl_add_u64 v[224:225], v[234:235], 0, s[36:37]
	s_mov_b32 m0, s58
	s_nop 0
	global_load_lds_dwordx4 v[224:225], off
	s_waitcnt vmcnt(8)
	s_waitcnt lgkmcnt(0)
	s_barrier
	s_setprio 1
	s_waitcnt lgkmcnt(0)
	v_mfma_f32_16x16x32_bf16 v[60:63], v[144:147], v[186:189], v[60:63]
	v_mfma_f32_16x16x32_bf16 v[56:59], v[160:163], v[186:189], v[56:59]
	v_mfma_f32_16x16x32_bf16 v[44:47], v[144:147], v[194:197], v[44:47]
	v_mfma_f32_16x16x32_bf16 v[40:43], v[160:163], v[194:197], v[40:43]
	v_mfma_f32_16x16x32_bf16 v[28:31], v[144:147], v[202:205], v[28:31]
	v_mfma_f32_16x16x32_bf16 v[24:27], v[160:163], v[202:205], v[24:27]
	v_mfma_f32_16x16x32_bf16 v[12:15], v[144:147], v[210:213], v[12:15]
	v_mfma_f32_16x16x32_bf16 v[8:11], v[160:163], v[210:213], v[8:11]
	v_mfma_f32_16x16x32_bf16 v[60:63], v[156:159], v[190:193], v[60:63]
	v_mfma_f32_16x16x32_bf16 v[56:59], v[164:167], v[190:193], v[56:59]
	v_mfma_f32_16x16x32_bf16 v[44:47], v[156:159], v[198:201], v[44:47]
	v_mfma_f32_16x16x32_bf16 v[40:43], v[164:167], v[198:201], v[40:43]
	v_mfma_f32_16x16x32_bf16 v[28:31], v[156:159], v[206:209], v[28:31]
	v_mfma_f32_16x16x32_bf16 v[24:27], v[164:167], v[206:209], v[24:27]
	v_mfma_f32_16x16x32_bf16 v[12:15], v[156:159], v[214:217], v[12:15]
	v_mfma_f32_16x16x32_bf16 v[8:11], v[164:167], v[214:217], v[8:11]
	s_setprio 0
	s_setprio 1
	v_mfma_f32_16x16x32_bf16 v[52:55], v[168:171], v[186:189], v[52:55]
	v_mfma_f32_16x16x32_bf16 v[48:51], v[176:179], v[186:189], v[48:51]
	v_mfma_f32_16x16x32_bf16 v[36:39], v[168:171], v[194:197], v[36:39]
	v_mfma_f32_16x16x32_bf16 v[32:35], v[176:179], v[194:197], v[32:35]
	v_mfma_f32_16x16x32_bf16 v[20:23], v[168:171], v[202:205], v[20:23]
	v_mfma_f32_16x16x32_bf16 v[16:19], v[176:179], v[202:205], v[16:19]
	v_mfma_f32_16x16x32_bf16 v[4:7], v[168:171], v[210:213], v[4:7]
	v_mfma_f32_16x16x32_bf16 v[0:3], v[176:179], v[210:213], v[0:3]
	v_mfma_f32_16x16x32_bf16 v[52:55], v[172:175], v[190:193], v[52:55]
	v_mfma_f32_16x16x32_bf16 v[48:51], v[180:183], v[190:193], v[48:51]
	v_mfma_f32_16x16x32_bf16 v[36:39], v[172:175], v[198:201], v[36:39]
	v_mfma_f32_16x16x32_bf16 v[32:35], v[180:183], v[198:201], v[32:35]
	v_mfma_f32_16x16x32_bf16 v[20:23], v[172:175], v[206:209], v[20:23]
	v_mfma_f32_16x16x32_bf16 v[16:19], v[180:183], v[206:209], v[16:19]
	v_mfma_f32_16x16x32_bf16 v[4:7], v[172:175], v[214:217], v[4:7]
	v_mfma_f32_16x16x32_bf16 v[0:3], v[180:183], v[214:217], v[0:3]
	s_add_u32 s4, s4, 0x100
	s_addc_u32 s5, s5, 0
	s_add_u32 s33, s33, 0x100
	s_addc_u32 s48, s48, 0
	s_cmp_ge_i32 s49, s59
	s_mov_b32 s46, s49
	s_setprio 0
	s_barrier
	s_cbranch_scc0 .LBB0_1112
